# phase4b compress-layer2 loop software-pipelined (double-buffered loads), post_z bias-sum loads batched, rope-slab loads hoisted above prior stores
# speedup vs baseline: 1.0364x; 1.0289x over previous
; #define VBID ((int)(blockIdx.x * 2) + HALF())
; DI void post_z(const Params& p, int layer) {
;     ...
;   {
;     const float* part = (const float*)(p.ws + O_HID);
;     float* bias = (float*)(p.ws + O_BIAS);
;     const int idx = VBID * 256 + tid_;
;     if (idx < 512) {
;       const int kv = idx >> 8, n = idx & 255;
;       float a = 0.f;
;       for (int kc = 0; kc < 64; ++kc) a += part[(kv * 64 + kc) * 256 + n];
;       bias[idx] = a;
;     }
;   }
.LBB0_181:
	s_or_b64 exec, exec, s[0:1]
	v_readfirstlane_b32 s0, v196
	s_and_b32 s0, s0, 0xffffff00
	v_readlane_b32 s1, v252, 9
	v_and_b32_e32 v0, 0xff, v196
	s_add_i32 s0, s0, s1
	s_barrier
	s_nop 0
	v_add_u32_e32 v2, s0, v0
	s_movk_i32 s0, 0x200
	v_cmp_gt_i32_e32 vcc, s0, v2
	s_and_saveexec_b64 s[0:1], vcc
	s_cbranch_execz .LBB0_185
	v_and_b32_e32 v3, 0xff, v0
	v_lshlrev_b32_e32 v4, 6, v2
	s_movk_i32 s2, 0xc000
	v_and_or_b32 v3, v4, s2, v3
	v_mov_b32_e32 v6, 0
	s_mov_b32 s2, 0
	v_lshlrev_b32_e32 v4, 2, v3
	v_mov_b32_e32 v5, v4
	global_load_dword v68, v5, s[26:27]
	global_load_dword v69, v5, s[26:27] offset:1024
	global_load_dword v70, v5, s[26:27] offset:2048
	global_load_dword v71, v5, s[26:27] offset:3072
	v_add_u32_e32 v5, 0x1000, v4
	global_load_dword v72, v5, s[26:27]
	global_load_dword v73, v5, s[26:27] offset:1024
	global_load_dword v74, v5, s[26:27] offset:2048
	global_load_dword v75, v5, s[26:27] offset:3072
	v_add_u32_e32 v5, 0x2000, v4
	global_load_dword v76, v5, s[26:27]
	global_load_dword v77, v5, s[26:27] offset:1024
	global_load_dword v78, v5, s[26:27] offset:2048
	global_load_dword v79, v5, s[26:27] offset:3072
	v_add_u32_e32 v5, 0x3000, v4
	global_load_dword v80, v5, s[26:27]
	global_load_dword v81, v5, s[26:27] offset:1024
	global_load_dword v82, v5, s[26:27] offset:2048
	global_load_dword v83, v5, s[26:27] offset:3072
	v_add_u32_e32 v5, 0x4000, v4
	global_load_dword v84, v5, s[26:27]
	global_load_dword v85, v5, s[26:27] offset:1024
	global_load_dword v86, v5, s[26:27] offset:2048
	global_load_dword v87, v5, s[26:27] offset:3072
	v_add_u32_e32 v5, 0x5000, v4
	global_load_dword v88, v5, s[26:27]
	global_load_dword v89, v5, s[26:27] offset:1024
	global_load_dword v90, v5, s[26:27] offset:2048
	global_load_dword v91, v5, s[26:27] offset:3072
	v_add_u32_e32 v5, 0x6000, v4
	global_load_dword v92, v5, s[26:27]
	global_load_dword v93, v5, s[26:27] offset:1024
	global_load_dword v94, v5, s[26:27] offset:2048
	global_load_dword v95, v5, s[26:27] offset:3072
	v_add_u32_e32 v5, 0x7000, v4
	global_load_dword v96, v5, s[26:27]
	global_load_dword v97, v5, s[26:27] offset:1024
	global_load_dword v98, v5, s[26:27] offset:2048
	global_load_dword v99, v5, s[26:27] offset:3072
	v_add_u32_e32 v5, 0x8000, v4
	global_load_dword v100, v5, s[26:27]
	global_load_dword v101, v5, s[26:27] offset:1024
	global_load_dword v102, v5, s[26:27] offset:2048
	global_load_dword v103, v5, s[26:27] offset:3072
	v_add_u32_e32 v5, 0x9000, v4
	global_load_dword v104, v5, s[26:27]
	global_load_dword v105, v5, s[26:27] offset:1024
	global_load_dword v106, v5, s[26:27] offset:2048
	global_load_dword v107, v5, s[26:27] offset:3072
	v_add_u32_e32 v5, 0xa000, v4
	global_load_dword v108, v5, s[26:27]
	global_load_dword v109, v5, s[26:27] offset:1024
	global_load_dword v110, v5, s[26:27] offset:2048
	global_load_dword v111, v5, s[26:27] offset:3072
	v_add_u32_e32 v5, 0xb000, v4
	global_load_dword v112, v5, s[26:27]
	global_load_dword v113, v5, s[26:27] offset:1024
	global_load_dword v114, v5, s[26:27] offset:2048
	global_load_dword v115, v5, s[26:27] offset:3072
	v_add_u32_e32 v5, 0xc000, v4
	global_load_dword v116, v5, s[26:27]
	global_load_dword v117, v5, s[26:27] offset:1024
	global_load_dword v118, v5, s[26:27] offset:2048
	global_load_dword v119, v5, s[26:27] offset:3072
	v_add_u32_e32 v5, 0xd000, v4
	global_load_dword v120, v5, s[26:27]
	global_load_dword v121, v5, s[26:27] offset:1024
	global_load_dword v122, v5, s[26:27] offset:2048
	global_load_dword v123, v5, s[26:27] offset:3072
	v_add_u32_e32 v5, 0xe000, v4
	global_load_dword v124, v5, s[26:27]
	global_load_dword v125, v5, s[26:27] offset:1024
	global_load_dword v126, v5, s[26:27] offset:2048
	global_load_dword v127, v5, s[26:27] offset:3072
	v_add_u32_e32 v5, 0xf000, v4
	global_load_dword v128, v5, s[26:27]
	global_load_dword v129, v5, s[26:27] offset:1024
	global_load_dword v130, v5, s[26:27] offset:2048
	global_load_dword v131, v5, s[26:27] offset:3072
	s_waitcnt vmcnt(0)
	v_add_f32_e32 v6, v6, v68
	v_add_f32_e32 v6, v6, v69
	v_add_f32_e32 v6, v6, v70
	v_add_f32_e32 v6, v6, v71
	v_add_f32_e32 v6, v6, v72
	v_add_f32_e32 v6, v6, v73
	v_add_f32_e32 v6, v6, v74
	v_add_f32_e32 v6, v6, v75
	v_add_f32_e32 v6, v6, v76
	v_add_f32_e32 v6, v6, v77
	v_add_f32_e32 v6, v6, v78
	v_add_f32_e32 v6, v6, v79
	v_add_f32_e32 v6, v6, v80
	v_add_f32_e32 v6, v6, v81
	v_add_f32_e32 v6, v6, v82
	v_add_f32_e32 v6, v6, v83
	v_add_f32_e32 v6, v6, v84
	v_add_f32_e32 v6, v6, v85
	v_add_f32_e32 v6, v6, v86
	v_add_f32_e32 v6, v6, v87
	v_add_f32_e32 v6, v6, v88
	v_add_f32_e32 v6, v6, v89
	v_add_f32_e32 v6, v6, v90
	v_add_f32_e32 v6, v6, v91
	v_add_f32_e32 v6, v6, v92
	v_add_f32_e32 v6, v6, v93
	v_add_f32_e32 v6, v6, v94
	v_add_f32_e32 v6, v6, v95
	v_add_f32_e32 v6, v6, v96
	v_add_f32_e32 v6, v6, v97
	v_add_f32_e32 v6, v6, v98
	v_add_f32_e32 v6, v6, v99
	v_add_f32_e32 v6, v6, v100
	v_add_f32_e32 v6, v6, v101
	v_add_f32_e32 v6, v6, v102
	v_add_f32_e32 v6, v6, v103
	v_add_f32_e32 v6, v6, v104
	v_add_f32_e32 v6, v6, v105
	v_add_f32_e32 v6, v6, v106
	v_add_f32_e32 v6, v6, v107
	v_add_f32_e32 v6, v6, v108
	v_add_f32_e32 v6, v6, v109
	v_add_f32_e32 v6, v6, v110
	v_add_f32_e32 v6, v6, v111
	v_add_f32_e32 v6, v6, v112
	v_add_f32_e32 v6, v6, v113
	v_add_f32_e32 v6, v6, v114
	v_add_f32_e32 v6, v6, v115
	v_add_f32_e32 v6, v6, v116
	v_add_f32_e32 v6, v6, v117
	v_add_f32_e32 v6, v6, v118
	v_add_f32_e32 v6, v6, v119
	v_add_f32_e32 v6, v6, v120
	v_add_f32_e32 v6, v6, v121
	v_add_f32_e32 v6, v6, v122
	v_add_f32_e32 v6, v6, v123
	v_add_f32_e32 v6, v6, v124
	v_add_f32_e32 v6, v6, v125
	v_add_f32_e32 v6, v6, v126
	v_add_f32_e32 v6, v6, v127
	v_add_f32_e32 v6, v6, v128
	v_add_f32_e32 v6, v6, v129
	v_add_f32_e32 v6, v6, v130
	v_add_f32_e32 v6, v6, v131
	v_readlane_b32 s2, v251, 53
	v_ashrrev_i32_e32 v3, 31, v2
	v_readlane_b32 s3, v251, 54
	s_nop 1
	v_lshl_add_u64 v[4:5], v[2:3], 2, s[2:3]
	global_store_dword v[4:5], v6, off

; DI bf16_t f2bf(float a) { return (bf16_t)(pack2(a, 0.f) & 0xffffu); }
; DI float bf2f(bf16_t h) { return __uint_as_float(((unsigned)h) << 16); }
; DI void post_z(const Params& p, int layer) {
;     ...
;       const int h = slab - 20;
;       const int colbase = C_RK + h * 128;
;       const float lg2 = log2f(1.f - exp2f(-5.f - (float)h));
;       float x1[32], x2[32];
; #pragma unroll
;       for (int i = 0; i < 32; ++i) {
;         const bf16_t* p1 = zr + (size_t)i * ZS + colbase + lane;
;         x1[i] = bf2f(p1[0]);
;         x2[i] = bf2f(p1[64]);
;       }
;       unsigned u1[32], u2[32];
; #pragma unroll
;       for (int i = 0; i < 32; ++i) {
;         bf16_t* p1 = zr + (size_t)i * ZS + colbase + lane;
;         float2 cs = rope[(spos + i) * 64 + lane];
;         float o1 = (x1[i] * cs.x - x2[i] * cs.y) * 0.08838834764831845f;
;         float o2 = (x1[i] * cs.y + x2[i] * cs.x) * 0.08838834764831845f;
;         p1[0] = f2bf(o1);
;         p1[64] = f2bf(o2);
;         float zeta = exp2f(lg2 * (float)(127 - ((spos + i) & 127)));
;         u1[i] = f2bf(o1 * zeta);
;         u2[i] = f2bf(o2 * zeta);
.LBB0_188:
	s_mov_b32 s0, 0x38e38e39
	v_mul_hi_i32 v0, v30, s0
	v_lshrrev_b32_e32 v2, 31, v0
	v_ashrrev_i32_e32 v0, 3, v0
	v_add_u32_e32 v43, v0, v2
	s_movk_i32 s0, 0xffdc
	v_mad_u64_u32 v[2:3], s[0:1], v43, s0, v[30:31]
	v_lshlrev_b32_e32 v45, 5, v43
	v_mov_b64_e32 v[4:5], s[16:17]
	v_ashrrev_i32_e32 v50, 8, v43
	v_and_b32_e32 v42, 0x1fe0, v45
	v_mad_i64_i32 v[6:7], s[0:1], v45, s35, v[4:5]
	v_cmp_gt_i32_e32 vcc, 32, v2
	s_and_saveexec_b64 s[0:1], vcc
	s_xor_b64 s[44:45], exec, s[0:1]
	s_cbranch_execz .LBB0_214
	v_cmp_lt_i32_e32 vcc, 11, v2
	s_and_saveexec_b64 s[0:1], vcc
	s_xor_b64 s[2:3], exec, s[0:1]
	s_cbranch_execz .LBB0_203
	v_subrev_u32_e32 v0, 24, v2
	v_cmp_lt_u32_e32 vcc, -9, v0
	s_and_saveexec_b64 s[0:1], vcc
	s_xor_b64 s[46:47], exec, s[0:1]
	s_cbranch_execz .LBB0_196
	v_lshlrev_b32_e32 v0, 3, v32
	v_cmp_lt_u32_e32 vcc, 19, v2
	v_lshl_or_b32 v4, v42, 9, v0
	s_and_saveexec_b64 s[0:1], vcc
	s_xor_b64 s[0:1], exec, s[0:1]
	s_cbranch_execz .LBB0_193
	v_subrev_u32_e32 v0, 20, v2
	v_cvt_f32_u32_e32 v0, v0
	s_movk_i32 s5, 0xee00
	s_mov_b32 s9, 0xc2fc0000
	v_mad_u64_u32 v[2:3], s[12:13], v43, s5, v[38:39]
	v_sub_f32_e32 v0, 0xc0a00000, v0
	v_cmp_gt_f32_e32 vcc, s9, v0
	s_mov_b32 s5, 0x800000
	v_readlane_b32 s20, v252, 10
	v_cndmask_b32_e32 v3, 0, v250, vcc
	v_add_f32_e32 v0, v0, v3
	v_exp_f32_e32 v0, v0
	v_cndmask_b32_e32 v3, 0, v162, vcc
	v_readlane_b32 s21, v252, 11
	v_mov_b32_e32 v51, 0x60
	v_ldexp_f32 v0, v0, v3
	v_sub_f32_e32 v5, 1.0, v0
	v_mov_b32_e32 v3, v1
	v_lshl_add_u64 v[2:3], v[2:3], 1, v[6:7]
	v_lshlrev_b32_e32 v0, 1, v32
	v_cmp_gt_f32_e32 vcc, s5, v5
	v_lshl_add_u64 v[82:83], v[2:3], 0, v[0:1]
	v_mov_b32_e32 v2, 0x42000000
	v_cndmask_b32_e64 v0, 0, 32, vcc
	v_ldexp_f32 v0, v5, v0
	v_log_f32_e32 v0, v0
	v_cndmask_b32_e32 v2, 0, v2, vcc
	v_mov_b32_e32 v5, v1
	s_movk_i32 s5, 0x7f
	v_sub_f32_e32 v0, v0, v2
	global_load_ushort v2, v[82:83], off offset:3632
	global_load_ushort v3, v[82:83], off offset:3760
	global_load_dwordx2 v[6:7], v4, s[20:21]
	v_lshl_add_u64 v[16:17], s[20:21], 0, v[4:5]
	v_readlane_b32 s12, v252, 26
	v_readlane_b32 s13, v252, 27
	s_waitcnt vmcnt(2)
	v_lshlrev_b32_e32 v2, 16, v2
	s_waitcnt vmcnt(1)
	v_lshlrev_b32_e32 v3, 16, v3
	s_waitcnt vmcnt(0)
	v_pk_mul_f32 v[8:9], v[6:7], v[2:3]
	v_pk_mul_f32 v[2:3], v[6:7], v[2:3] op_sel:[0,1] op_sel_hi:[1,0]
	v_sub_f32_e32 v52, v8, v9
	v_add_f32_e32 v5, v2, v3
	v_bitop3_b32 v2, v45, s5, v51 bitop3:0x6c
	v_cvt_f32_ubyte0_e32 v2, v2
	v_mul_f32_e32 v3, v0, v2
	v_cmp_gt_f32_e32 vcc, s9, v3
	s_movk_i32 s5, 0x7e
	v_mul_f32_e32 v90, 0x3db504f3, v52
	v_cndmask_b32_e32 v3, 0, v250, vcc
	v_fmac_f32_e32 v3, v0, v2
	v_exp_f32_e32 v2, v3
	v_cndmask_b32_e32 v3, 0, v162, vcc
	v_mul_f32_e32 v190, 0x3db504f3, v5
	v_cvt_pk_bf16_f32 v174, v90, s0
	v_ldexp_f32 v26, v2, v3
	v_bitop3_b32 v2, v45, s5, v51 bitop3:0x6c
	v_cvt_f32_ubyte0_e32 v2, v2
	v_mul_f32_e32 v3, v0, v2
	v_cmp_gt_f32_e32 vcc, s9, v3
	s_movk_i32 s5, 0x7d
	v_cvt_pk_bf16_f32 v5, v190, s0
	v_cndmask_b32_e32 v3, 0, v250, vcc
	v_fmac_f32_e32 v3, v0, v2
	v_exp_f32_e32 v2, v3
	v_cndmask_b32_e32 v3, 0, v162, vcc
	v_ldexp_f32 v2, v2, v3
	v_bitop3_b32 v3, v45, s5, v51 bitop3:0x6c
	v_cvt_f32_ubyte0_e32 v3, v3
	v_mul_f32_e32 v6, v0, v3
	v_cmp_gt_f32_e32 vcc, s9, v6
	s_movk_i32 s5, 0x7c
	s_nop 0
	v_cndmask_b32_e32 v6, 0, v250, vcc
	v_fmac_f32_e32 v6, v0, v3
	v_exp_f32_e32 v3, v6
	v_cndmask_b32_e32 v6, 0, v162, vcc
	v_ldexp_f32 v27, v3, v6
	v_bitop3_b32 v3, v45, s5, v51 bitop3:0x6c
	v_cvt_f32_ubyte0_e32 v3, v3
	v_mul_f32_e32 v6, v0, v3
	v_cmp_gt_f32_e32 vcc, s9, v6
	s_movk_i32 s5, 0x7b
	s_nop 0
	v_cndmask_b32_e32 v6, 0, v250, vcc
	v_fmac_f32_e32 v6, v0, v3
	v_exp_f32_e32 v3, v6
	v_cndmask_b32_e32 v6, 0, v162, vcc
	v_ldexp_f32 v3, v3, v6
	v_bitop3_b32 v6, v45, s5, v51 bitop3:0x6c
	v_cvt_f32_ubyte0_e32 v6, v6
	v_mul_f32_e32 v7, v0, v6
	v_cmp_gt_f32_e32 vcc, s9, v7
	s_movk_i32 s5, 0x7a
	s_nop 0
	v_cndmask_b32_e32 v7, 0, v250, vcc
	v_fmac_f32_e32 v7, v0, v6
	v_exp_f32_e32 v6, v7
	v_cndmask_b32_e32 v7, 0, v162, vcc
	v_ldexp_f32 v68, v6, v7
	v_bitop3_b32 v6, v45, s5, v51 bitop3:0x6c
	v_cvt_f32_ubyte0_e32 v6, v6
	v_mul_f32_e32 v7, v0, v6
	v_cmp_gt_f32_e32 vcc, s9, v7
	s_movk_i32 s5, 0x79
	s_nop 0
	v_cndmask_b32_e32 v7, 0, v250, vcc
	v_fmac_f32_e32 v7, v0, v6
	v_exp_f32_e32 v6, v7
	v_cndmask_b32_e32 v7, 0, v162, vcc
	v_ldexp_f32 v28, v6, v7
	v_bitop3_b32 v6, v45, s5, v51 bitop3:0x6c
	v_cvt_f32_ubyte0_e32 v6, v6
	v_mul_f32_e32 v7, v0, v6
	v_cmp_gt_f32_e32 vcc, s9, v7
	s_movk_i32 s5, 0x78
	s_nop 0
	v_cndmask_b32_e32 v7, 0, v250, vcc
	v_fmac_f32_e32 v7, v0, v6
	v_exp_f32_e32 v6, v7
	v_cndmask_b32_e32 v7, 0, v162, vcc
	v_ldexp_f32 v69, v6, v7
	v_bitop3_b32 v6, v45, s5, v51 bitop3:0x6c
	v_cvt_f32_ubyte0_e32 v6, v6
	v_mul_f32_e32 v7, v0, v6
	v_cmp_gt_f32_e32 vcc, s9, v7
	s_movk_i32 s5, 0x77
	s_nop 0
	v_cndmask_b32_e32 v7, 0, v250, vcc
	v_fmac_f32_e32 v7, v0, v6
	v_exp_f32_e32 v6, v7
	v_cndmask_b32_e32 v7, 0, v162, vcc
	v_ldexp_f32 v29, v6, v7
	v_bitop3_b32 v6, v45, s5, v51 bitop3:0x6c
	v_cvt_f32_ubyte0_e32 v6, v6
	v_mul_f32_e32 v7, v0, v6
	v_cmp_gt_f32_e32 vcc, s9, v7
	s_movk_i32 s5, 0x76
	s_nop 0
	v_cndmask_b32_e32 v7, 0, v250, vcc
	v_fmac_f32_e32 v7, v0, v6
	v_exp_f32_e32 v6, v7
	v_cndmask_b32_e32 v7, 0, v162, vcc
	v_ldexp_f32 v10, v6, v7
	v_bitop3_b32 v6, v45, s5, v51 bitop3:0x6c
	v_cvt_f32_ubyte0_e32 v6, v6
	v_mul_f32_e32 v7, v0, v6
	v_cmp_gt_f32_e32 vcc, s9, v7
	s_movk_i32 s5, 0x75
	s_nop 0
	v_cndmask_b32_e32 v7, 0, v250, vcc
	v_fmac_f32_e32 v7, v0, v6
	v_exp_f32_e32 v6, v7
	v_cndmask_b32_e32 v7, 0, v162, vcc
	v_ldexp_f32 v6, v6, v7
	v_bitop3_b32 v7, v45, s5, v51 bitop3:0x6c
	v_cvt_f32_ubyte0_e32 v7, v7
	v_mul_f32_e32 v8, v0, v7
; DI bf16_t f2bf(float a) { return (bf16_t)(pack2(a, 0.f) & 0xffffu); }
; DI void post_z(const Params& p, int layer) {
;     ...
;       for (int i = 0; i < 32; ++i) {
;         bf16_t* p1 = zr + (size_t)i * ZS + colbase + lane;
;         float2 cs = rope[(spos + i) * 64 + lane];
;         float o1 = (x1[i] * cs.x - x2[i] * cs.y) * 0.08838834764831845f;
;         float o2 = (x1[i] * cs.y + x2[i] * cs.x) * 0.08838834764831845f;
;         p1[0] = f2bf(o1);
;         p1[64] = f2bf(o2);
;         float zeta = exp2f(lg2 * (float)(127 - ((spos + i) & 127)));
;         u1[i] = f2bf(o1 * zeta);
;         u2[i] = f2bf(o2 * zeta);
	v_cmp_gt_f32_e32 vcc, s9, v8
	s_movk_i32 s5, 0x74
	s_nop 0
	v_cndmask_b32_e32 v8, 0, v250, vcc
	v_fmac_f32_e32 v8, v0, v7
	v_exp_f32_e32 v7, v8
	v_cndmask_b32_e32 v8, 0, v162, vcc
	v_ldexp_f32 v11, v7, v8
	v_bitop3_b32 v7, v45, s5, v51 bitop3:0x6c
	v_cvt_f32_ubyte0_e32 v7, v7
	v_mul_f32_e32 v8, v0, v7
	v_cmp_gt_f32_e32 vcc, s9, v8
	s_movk_i32 s5, 0x73
	s_nop 0
	v_cndmask_b32_e32 v8, 0, v250, vcc
	v_fmac_f32_e32 v8, v0, v7
	v_exp_f32_e32 v7, v8
	v_cndmask_b32_e32 v8, 0, v162, vcc
	v_ldexp_f32 v7, v7, v8
	v_bitop3_b32 v8, v45, s5, v51 bitop3:0x6c
	v_cvt_f32_ubyte0_e32 v8, v8
	v_mul_f32_e32 v9, v0, v8
	v_cmp_gt_f32_e32 vcc, s9, v9
	s_movk_i32 s5, 0x72
	s_nop 0
	v_cndmask_b32_e32 v9, 0, v250, vcc
	v_fmac_f32_e32 v9, v0, v8
	v_exp_f32_e32 v8, v9
	v_cndmask_b32_e32 v9, 0, v162, vcc
	v_ldexp_f32 v12, v8, v9
	v_bitop3_b32 v8, v45, s5, v51 bitop3:0x6c
	v_cvt_f32_ubyte0_e32 v8, v8
	v_mul_f32_e32 v9, v0, v8
	v_cmp_gt_f32_e32 vcc, s9, v9
	s_movk_i32 s5, 0x71
	s_nop 0
	v_cndmask_b32_e32 v9, 0, v250, vcc
	v_fmac_f32_e32 v9, v0, v8
	v_exp_f32_e32 v8, v9
	v_cndmask_b32_e32 v9, 0, v162, vcc
	v_ldexp_f32 v8, v8, v9
	v_bitop3_b32 v9, v45, s5, v51 bitop3:0x6c
	v_cvt_f32_ubyte0_e32 v9, v9
	v_mul_f32_e32 v13, v0, v9
	v_cmp_gt_f32_e32 vcc, s9, v13
	s_movk_i32 s5, 0x70
	s_nop 0
	v_cndmask_b32_e32 v13, 0, v250, vcc
	v_fmac_f32_e32 v13, v0, v9
	v_exp_f32_e32 v9, v13
	v_cndmask_b32_e32 v13, 0, v162, vcc
	v_ldexp_f32 v13, v9, v13
	v_bitop3_b32 v9, v45, s5, v51 bitop3:0x6c
	v_cvt_f32_ubyte0_e32 v9, v9
	v_mul_f32_e32 v14, v0, v9
	v_cmp_gt_f32_e32 vcc, s9, v14
	s_movk_i32 s5, 0x6f
	s_nop 0
	v_cndmask_b32_e32 v14, 0, v250, vcc
	v_fmac_f32_e32 v14, v0, v9
	v_exp_f32_e32 v9, v14
	v_cndmask_b32_e32 v14, 0, v162, vcc
	v_ldexp_f32 v9, v9, v14
	v_bitop3_b32 v14, v45, s5, v51 bitop3:0x6c
	v_cvt_f32_ubyte0_e32 v14, v14
	v_mul_f32_e32 v15, v0, v14
	v_cmp_gt_f32_e32 vcc, s9, v15
	s_movk_i32 s5, 0x6e
	s_nop 0
	v_cndmask_b32_e32 v15, 0, v250, vcc
	v_fmac_f32_e32 v15, v0, v14
	v_exp_f32_e32 v14, v15
	v_cndmask_b32_e32 v15, 0, v162, vcc
	v_ldexp_f32 v18, v14, v15
	v_bitop3_b32 v14, v45, s5, v51 bitop3:0x6c
	v_cvt_f32_ubyte0_e32 v14, v14
	v_mul_f32_e32 v15, v0, v14
	v_cmp_gt_f32_e32 vcc, s9, v15
	s_movk_i32 s5, 0x6d
	s_nop 0
	v_cndmask_b32_e32 v15, 0, v250, vcc
	v_fmac_f32_e32 v15, v0, v14
	v_exp_f32_e32 v14, v15
	v_cndmask_b32_e32 v15, 0, v162, vcc
	v_ldexp_f32 v14, v14, v15
	v_bitop3_b32 v15, v45, s5, v51 bitop3:0x6c
	v_cvt_f32_ubyte0_e32 v15, v15
	v_mul_f32_e32 v19, v0, v15
	v_cmp_gt_f32_e32 vcc, s9, v19
	s_movk_i32 s5, 0x6c
	s_nop 0
	v_cndmask_b32_e32 v19, 0, v250, vcc
	v_fmac_f32_e32 v19, v0, v15
	v_exp_f32_e32 v15, v19
	v_cndmask_b32_e32 v19, 0, v162, vcc
	v_ldexp_f32 v19, v15, v19
	v_bitop3_b32 v15, v45, s5, v51 bitop3:0x6c
	v_cvt_f32_ubyte0_e32 v15, v15
	v_mul_f32_e32 v20, v0, v15
	v_cmp_gt_f32_e32 vcc, s9, v20
	s_movk_i32 s5, 0x6b
	s_nop 0
	v_cndmask_b32_e32 v20, 0, v250, vcc
	v_fmac_f32_e32 v20, v0, v15
	v_exp_f32_e32 v15, v20
	v_cndmask_b32_e32 v20, 0, v162, vcc
	v_ldexp_f32 v15, v15, v20
	v_bitop3_b32 v20, v45, s5, v51 bitop3:0x6c
	v_cvt_f32_ubyte0_e32 v20, v20
	v_mul_f32_e32 v21, v0, v20
	v_cmp_gt_f32_e32 vcc, s9, v21
	s_movk_i32 s5, 0x6a
	s_nop 0
	v_cndmask_b32_e32 v21, 0, v250, vcc
	v_fmac_f32_e32 v21, v0, v20
	v_exp_f32_e32 v20, v21
	v_cndmask_b32_e32 v21, 0, v162, vcc
	v_ldexp_f32 v48, v20, v21
	v_bitop3_b32 v20, v45, s5, v51 bitop3:0x6c
	v_cvt_f32_ubyte0_e32 v20, v20
	v_mul_f32_e32 v21, v0, v20
	v_cmp_gt_f32_e32 vcc, s9, v21
	s_movk_i32 s5, 0x69
	s_nop 0
	v_cndmask_b32_e32 v21, 0, v250, vcc
	v_fmac_f32_e32 v21, v0, v20
	v_exp_f32_e32 v20, v21
	v_cndmask_b32_e32 v21, 0, v162, vcc
	v_ldexp_f32 v20, v20, v21
	v_bitop3_b32 v21, v45, s5, v51 bitop3:0x6c
	v_cvt_f32_ubyte0_e32 v21, v21
	v_mul_f32_e32 v22, v0, v21
	v_cmp_gt_f32_e32 vcc, s9, v22
	s_movk_i32 s5, 0x68
	s_nop 0
	v_cndmask_b32_e32 v22, 0, v250, vcc
	v_fmac_f32_e32 v22, v0, v21
	v_exp_f32_e32 v21, v22
	v_cndmask_b32_e32 v22, 0, v162, vcc
	v_ldexp_f32 v49, v21, v22
	v_bitop3_b32 v21, v45, s5, v51 bitop3:0x6c
	v_cvt_f32_ubyte0_e32 v21, v21
	v_mul_f32_e32 v22, v0, v21
	v_cmp_gt_f32_e32 vcc, s9, v22
	s_movk_i32 s5, 0x67
	s_nop 0
	v_cndmask_b32_e32 v22, 0, v250, vcc
	v_fmac_f32_e32 v22, v0, v21
	v_exp_f32_e32 v21, v22
	v_cndmask_b32_e32 v22, 0, v162, vcc
	v_ldexp_f32 v21, v21, v22
	v_bitop3_b32 v22, v45, s5, v51 bitop3:0x6c
	v_cvt_f32_ubyte0_e32 v22, v22
	v_mul_f32_e32 v23, v0, v22
	v_cmp_gt_f32_e32 vcc, s9, v23
	s_movk_i32 s5, 0x66
	s_nop 0
	v_cndmask_b32_e32 v23, 0, v250, vcc
	v_fmac_f32_e32 v23, v0, v22
	v_exp_f32_e32 v22, v23
	v_cndmask_b32_e32 v23, 0, v162, vcc
	v_ldexp_f32 v24, v22, v23
	v_bitop3_b32 v22, v45, s5, v51 bitop3:0x6c
	v_cvt_f32_ubyte0_e32 v22, v22
	v_mul_f32_e32 v23, v0, v22
	v_cmp_gt_f32_e32 vcc, s9, v23
	s_movk_i32 s5, 0x65
	s_nop 0
	v_cndmask_b32_e32 v23, 0, v250, vcc
	v_fmac_f32_e32 v23, v0, v22
	v_exp_f32_e32 v22, v23
	v_cndmask_b32_e32 v23, 0, v162, vcc
	v_ldexp_f32 v22, v22, v23
	v_bitop3_b32 v23, v45, s5, v51 bitop3:0x6c
	v_cvt_f32_ubyte0_e32 v23, v23
	v_mul_f32_e32 v25, v0, v23
	v_cmp_gt_f32_e32 vcc, s9, v25
	s_movk_i32 s5, 0x64
	s_nop 0
	v_cndmask_b32_e32 v25, 0, v250, vcc
	v_fmac_f32_e32 v25, v0, v23
	v_exp_f32_e32 v23, v25
	v_cndmask_b32_e32 v25, 0, v162, vcc
	v_ldexp_f32 v25, v23, v25
	v_bitop3_b32 v23, v45, s5, v51 bitop3:0x6c
	v_cvt_f32_ubyte0_e32 v23, v23
	v_mul_f32_e32 v44, v0, v23
	v_cmp_gt_f32_e32 vcc, s9, v44
	s_movk_i32 s5, 0x63
	s_nop 0
	v_cndmask_b32_e32 v44, 0, v250, vcc
	v_fmac_f32_e32 v44, v0, v23
	v_exp_f32_e32 v23, v44
	v_cndmask_b32_e32 v44, 0, v162, vcc
	v_ldexp_f32 v23, v23, v44
	v_bitop3_b32 v44, v45, s5, v51 bitop3:0x6c
	v_cvt_f32_ubyte0_e32 v44, v44
; DI float bf2f(bf16_t h) { return __uint_as_float(((unsigned)h) << 16); }
; DI void post_z(const Params& p, int layer) {
;     ...
; #pragma unroll
;       for (int i = 0; i < 32; ++i) {
;         const bf16_t* p1 = zr + (size_t)i * ZS + colbase + lane;
;         x1[i] = bf2f(p1[0]);
;         x2[i] = bf2f(p1[64]);
;       }
;     ...
;       bf16_t* d1 = kzT + ((size_t)((b * 4 + h) * 128 + lane)) * TS + spos;
	v_mul_f32_e32 v46, v0, v44
	v_cmp_gt_f32_e32 vcc, s9, v46
	s_movk_i32 s5, 0x62
	s_nop 0
	v_cndmask_b32_e32 v46, 0, v250, vcc
	v_fmac_f32_e32 v46, v0, v44
	v_exp_f32_e32 v44, v46
	v_cndmask_b32_e32 v46, 0, v162, vcc
	v_ldexp_f32 v46, v44, v46
	v_bitop3_b32 v44, v45, s5, v51 bitop3:0x6c
	v_cvt_f32_ubyte0_e32 v44, v44
	v_mul_f32_e32 v47, v0, v44
	v_cmp_gt_f32_e32 vcc, s9, v47
	s_movk_i32 s5, 0x61
	s_nop 0
	v_cndmask_b32_e32 v47, 0, v250, vcc
	v_fmac_f32_e32 v47, v0, v44
	v_exp_f32_e32 v44, v47
	v_cndmask_b32_e32 v47, 0, v162, vcc
	v_ldexp_f32 v44, v44, v47
	v_bitop3_b32 v47, v45, s5, v51 bitop3:0x6c
	v_cvt_f32_ubyte0_e32 v47, v47
	v_mul_f32_e32 v51, v0, v47
	v_cmp_gt_f32_e32 vcc, s9, v51
	s_movk_i32 s5, 0x60
	v_bitop3_b32 v45, v45, s5, v45 bitop3:0xc
	v_cndmask_b32_e32 v51, 0, v250, vcc
	v_fmac_f32_e32 v51, v0, v47
	v_exp_f32_e32 v47, v51
	v_cndmask_b32_e32 v51, 0, v162, vcc
	v_cvt_f32_ubyte0_e32 v45, v45
	s_movk_i32 s5, 0x1200
	v_ldexp_f32 v47, v47, v51
	v_mul_f32_e32 v51, v0, v45
	v_cmp_gt_f32_e32 vcc, s9, v51
	v_mul_lo_u32 v43, v43, s5
	s_movk_i32 s5, 0x4080
	v_cndmask_b32_e32 v51, 0, v250, vcc
	v_fmac_f32_e32 v51, v0, v45
	v_exp_f32_e32 v0, v51
	v_cndmask_b32_e32 v45, 0, v162, vcc
	s_mov_b32 s9, 0x800000
	v_ldexp_f32 v45, v0, v45
	v_lshlrev_b32_e32 v0, 9, v50
	v_sub_u32_e32 v0, v0, v43
	v_add3_u32 v0, v32, v38, v0
	v_mov_b64_e32 v[50:51], s[12:13]
	v_mad_i64_i32 v[50:51], s[12:13], v0, s5, v[50:51]
	s_movk_i32 s12, 0x3000
	s_nop 0
	v_add_co_u32_e32 v94, vcc, s12, v82
	s_movk_i32 s5, 0x6000
	s_nop 0
	v_addc_co_u32_e32 v95, vcc, 0, v83, vcc
	v_add_co_u32_e32 v122, vcc, s5, v82
	s_mov_b32 s5, 0x8000
	s_nop 0
	v_addc_co_u32_e32 v123, vcc, 0, v83, vcc
	v_add_co_u32_e32 v120, vcc, s5, v82
	s_mov_b32 s5, 0xb000
	s_nop 0
	v_addc_co_u32_e32 v121, vcc, 0, v83, vcc
	v_add_co_u32_e32 v118, vcc, s5, v82
	s_mov_b32 s5, 0xe000
	s_nop 0
	v_addc_co_u32_e32 v119, vcc, 0, v83, vcc
	v_add_co_u32_e32 v116, vcc, s5, v82
	s_mov_b32 s5, 0x10000
	s_nop 0
	v_addc_co_u32_e32 v117, vcc, 0, v83, vcc
	v_add_co_u32_e32 v114, vcc, s5, v82
	s_mov_b32 s5, 0x13000
	s_nop 0
	v_addc_co_u32_e32 v115, vcc, 0, v83, vcc
	v_add_co_u32_e32 v112, vcc, s5, v82
	s_mov_b32 s5, 0x15000
	s_nop 0
	v_addc_co_u32_e32 v113, vcc, 0, v83, vcc
	v_add_co_u32_e32 v110, vcc, s5, v82
	s_mov_b32 s5, 0x16000
	s_nop 0
	v_addc_co_u32_e32 v111, vcc, 0, v83, vcc
	v_add_co_u32_e32 v108, vcc, s5, v82
	s_mov_b32 s5, 0x18000
	s_nop 0
	v_addc_co_u32_e32 v109, vcc, 0, v83, vcc
	v_add_co_u32_e32 v106, vcc, s5, v82
	s_mov_b32 s5, 0x1b000
	s_nop 0
	v_addc_co_u32_e32 v107, vcc, 0, v83, vcc
	v_add_co_u32_e32 v104, vcc, s5, v82
	s_mov_b32 s5, 0x1d000
	s_nop 0
	v_addc_co_u32_e32 v105, vcc, 0, v83, vcc
	v_add_co_u32_e32 v102, vcc, s5, v82
	s_mov_b32 s5, 0x20000
	s_nop 0
	v_addc_co_u32_e32 v103, vcc, 0, v83, vcc
	v_add_co_u32_e32 v100, vcc, s5, v82
	s_mov_b32 s5, 0x23000
	s_nop 0
	v_addc_co_u32_e32 v101, vcc, 0, v83, vcc
	v_add_co_u32_e32 v98, vcc, s5, v82
	s_mov_b32 s5, 0x25000
	s_nop 0
	v_addc_co_u32_e32 v99, vcc, 0, v83, vcc
	v_add_co_u32_e32 v96, vcc, s5, v82
	s_mov_b32 s5, 0x28000
	s_nop 0
	v_addc_co_u32_e32 v97, vcc, 0, v83, vcc
	v_add_co_u32_e32 v92, vcc, s5, v82
	s_mov_b32 s5, 0x2b000
	s_nop 0
	v_addc_co_u32_e32 v93, vcc, 0, v83, vcc
	v_add_co_u32_e32 v88, vcc, s5, v82
	s_mov_b32 s5, 0x2d000
	s_nop 0
	v_addc_co_u32_e32 v89, vcc, 0, v83, vcc
	v_add_co_u32_e32 v86, vcc, s5, v82
	s_mov_b32 s5, 0x30000
	s_nop 0
	v_addc_co_u32_e32 v87, vcc, 0, v83, vcc
	v_add_co_u32_e32 v84, vcc, s5, v82
	s_mov_b32 s5, 0x33000
	s_nop 0
	v_addc_co_u32_e32 v85, vcc, 0, v83, vcc
	v_add_co_u32_e32 v78, vcc, s5, v82
	s_mov_b32 s5, 0x32000
	s_nop 0
	v_addc_co_u32_e32 v79, vcc, 0, v83, vcc
	v_add_co_u32_e32 v80, vcc, s5, v82
	s_mov_b32 s5, 0x35000
	s_nop 0
	v_addc_co_u32_e32 v81, vcc, 0, v83, vcc
	v_add_co_u32_e32 v76, vcc, s5, v82
	s_mov_b32 s5, 0x38000
	s_nop 0
	v_addc_co_u32_e32 v77, vcc, 0, v83, vcc
	v_add_co_u32_e32 v74, vcc, s5, v82
	s_mov_b32 s5, 0x3a000
	s_nop 0
	v_addc_co_u32_e32 v75, vcc, 0, v83, vcc
	v_add_co_u32_e32 v72, vcc, s5, v82
	s_mov_b32 s5, 0x3d000
	s_nop 0
	v_addc_co_u32_e32 v73, vcc, 0, v83, vcc
	v_add_co_u32_e32 v70, vcc, s5, v82
	s_mov_b32 s5, 0x40000
	s_nop 0
	v_addc_co_u32_e32 v71, vcc, 0, v83, vcc
	v_add_co_u32_e32 v66, vcc, s5, v82
	s_mov_b32 s5, 0x42000
	s_nop 0
	v_addc_co_u32_e32 v67, vcc, 0, v83, vcc
	v_add_co_u32_e32 v64, vcc, s5, v82
	s_mov_b32 s5, 0x45000
	s_nop 0
	v_addc_co_u32_e32 v65, vcc, 0, v83, vcc
	v_add_co_u32_e32 v62, vcc, s5, v82
	s_mov_b32 s5, 0x48000
	s_nop 0
	v_addc_co_u32_e32 v63, vcc, 0, v83, vcc
	v_add_co_u32_e32 v60, vcc, s5, v82
	s_mov_b32 s5, 0x4a000
	s_nop 0
	v_addc_co_u32_e32 v61, vcc, 0, v83, vcc
	v_add_co_u32_e32 v58, vcc, s5, v82
	s_mov_b32 s5, 0x4d000
	s_nop 0
	v_addc_co_u32_e32 v59, vcc, 0, v83, vcc
	v_add_co_u32_e32 v56, vcc, s5, v82
	s_mov_b32 s5, 0x50000
	s_nop 0
	v_addc_co_u32_e32 v57, vcc, 0, v83, vcc
	v_add_co_u32_e32 v52, vcc, s5, v82
	s_mov_b32 s5, 0x4f000
	s_nop 0
	v_addc_co_u32_e32 v53, vcc, 0, v83, vcc
	v_add_co_u32_e32 v54, vcc, s5, v82
	v_lshlrev_b32_e32 v0, 1, v42
	s_nop 0
	v_addc_co_u32_e32 v55, vcc, 0, v83, vcc
	s_mov_b32 s5, 0x52000
	v_lshl_add_u64 v[42:43], v[50:51], 0, v[0:1]
	v_add_co_u32_e32 v50, vcc, s5, v82
	global_load_ushort v91, v[94:95], off offset:2272
	global_load_ushort v158, v[94:95], off offset:2144
	v_addc_co_u32_e32 v51, vcc, 0, v83, vcc
	global_load_ushort v187, v[122:123], off offset:784
	global_load_ushort v188, v[122:123], off offset:656
	global_load_ushort v185, v[120:121], off offset:3392
	global_load_ushort v186, v[120:121], off offset:3264
	global_load_ushort v183, v[118:119], off offset:1776
	global_load_ushort v184, v[118:119], off offset:1904
; DI bf16_t f2bf(float a) { return (bf16_t)(pack2(a, 0.f) & 0xffffu); }
; DI void post_z(const Params& p, int layer) {
;     ...
;       for (int i = 0; i < 32; ++i) {
;         bf16_t* p1 = zr + (size_t)i * ZS + colbase + lane;
;         float2 cs = rope[(spos + i) * 64 + lane];
;         float o1 = (x1[i] * cs.x - x2[i] * cs.y) * 0.08838834764831845f;
;         float o2 = (x1[i] * cs.y + x2[i] * cs.x) * 0.08838834764831845f;
;         p1[0] = f2bf(o1);
;         p1[64] = f2bf(o2);
;         float zeta = exp2f(lg2 * (float)(127 - ((spos + i) & 127)));
;         u1[i] = f2bf(o1 * zeta);
;         u2[i] = f2bf(o2 * zeta);
;       }
	global_load_ushort v181, v[116:117], off offset:416
	global_load_ushort v182, v[116:117], off offset:288
	global_load_ushort v179, v[114:115], off offset:3024
	global_load_ushort v180, v[114:115], off offset:2896
	global_load_ushort v177, v[112:113], off offset:1536
	global_load_ushort v178, v[112:113], off offset:1408
	global_load_ushort v175, v[110:111], off offset:4016
	global_load_ushort v176, v[108:109], off offset:48
	global_load_ushort v172, v[106:107], off offset:2656
	global_load_ushort v173, v[106:107], off offset:2528
	global_load_ushort v170, v[104:105], off offset:1168
	global_load_ushort v171, v[104:105], off offset:1040
	global_load_ushort v168, v[102:103], off offset:3776
	global_load_ushort v169, v[102:103], off offset:3648
	global_load_ushort v166, v[100:101], off offset:2160
	global_load_ushort v167, v[100:101], off offset:2288
	global_load_ushort v164, v[98:99], off offset:800
	global_load_ushort v165, v[98:99], off offset:672
	global_load_ushort v161, v[96:97], off offset:3408
	global_load_ushort v163, v[96:97], off offset:3280
	global_load_ushort v159, v[92:93], off offset:1920
	global_load_ushort v160, v[92:93], off offset:1792
	global_load_ushort v156, v[88:89], off offset:304
	global_load_ushort v157, v[88:89], off offset:432
	global_load_ushort v154, v[86:87], off offset:3040
	global_load_ushort v155, v[86:87], off offset:2912
	global_load_ushort v152, v[84:85], off offset:1552
	global_load_ushort v153, v[84:85], off offset:1424
	global_load_ushort v150, v[78:79], off offset:64
	global_load_ushort v151, v[80:81], off offset:4032
	global_load_ushort v148, v[76:77], off offset:2544
	global_load_ushort v149, v[76:77], off offset:2672
	global_load_ushort v146, v[74:75], off offset:1184
	global_load_ushort v147, v[74:75], off offset:1056
	global_load_ushort v144, v[72:73], off offset:3792
	global_load_ushort v145, v[72:73], off offset:3664
	global_load_ushort v142, v[70:71], off offset:2304
	global_load_ushort v143, v[70:71], off offset:2176
	global_load_ushort v140, v[66:67], off offset:688
	global_load_ushort v141, v[66:67], off offset:816
	global_load_ushort v138, v[64:65], off offset:3424
	global_load_ushort v139, v[64:65], off offset:3296
	global_load_ushort v136, v[62:63], off offset:1936
	global_load_ushort v137, v[62:63], off offset:1808
	global_load_ushort v134, v[60:61], off offset:448
	global_load_ushort v135, v[60:61], off offset:320
	global_load_ushort v132, v[58:59], off offset:2928
	global_load_ushort v133, v[58:59], off offset:3056
	global_load_ushort v130, v[56:57], off offset:1568
	global_load_ushort v131, v[56:57], off offset:1440
	global_load_ushort v128, v[52:53], off offset:80
	global_load_ushort v129, v[54:55], off offset:4048
	global_load_ushort v0, v[50:51], off offset:2688
	global_load_ushort v127, v[50:51], off offset:2560
	s_movk_i32 s5, 0x1000
	global_store_short v[82:83], v174, off offset:3632
	global_store_short v[82:83], v5, off offset:3760
	global_load_dwordx2 v[192:193], v4, s[20:21] offset:512
	s_waitcnt vmcnt(62)
	v_lshlrev_b32_e32 v82, 16, v91
	v_lshlrev_b32_e32 v83, 16, v158
	s_waitcnt vmcnt(0)
	v_pk_mul_f32 v[194:195], v[192:193], v[82:83] op_sel:[0,1] op_sel_hi:[1,0]
	s_nop 0
	v_sub_f32_e32 v5, v194, v195
	v_pk_mul_f32 v[82:83], v[192:193], v[82:83]
	v_mul_f32_e32 v194, 0x3db504f3, v5
	v_add_f32_e32 v5, v82, v83
	v_mul_f32_e32 v82, 0x3db504f3, v5
	v_cvt_pk_bf16_f32 v5, v194, s0
	global_store_short v[94:95], v5, off offset:2144
	v_cvt_pk_bf16_f32 v5, v82, s0
	global_store_short v[94:95], v5, off offset:2272
	v_lshlrev_b32_e32 v95, 16, v188
	global_load_dwordx2 v[188:189], v4, s[20:21] offset:1024
	v_lshlrev_b32_e32 v94, 16, v187
	s_waitcnt vmcnt(0)
	v_pk_mul_f32 v[192:193], v[188:189], v[94:95] op_sel:[0,1] op_sel_hi:[1,0]
	s_nop 0
	v_sub_f32_e32 v5, v192, v193
	v_pk_mul_f32 v[94:95], v[188:189], v[94:95]
	v_mul_f32_e32 v91, 0x3db504f3, v5
	v_add_f32_e32 v5, v94, v95
	v_mul_f32_e32 v191, 0x3db504f3, v5
	v_cvt_pk_bf16_f32 v5, v91, s0
	global_store_short v[122:123], v5, off offset:656
	v_cvt_pk_bf16_f32 v5, v191, s0
	global_store_short v[122:123], v5, off offset:784
	v_pk_mul_f32 v[90:91], v[26:27], v[90:91]
	v_pk_mul_f32 v[26:27], v[26:27], v[190:191]
	v_cvt_pk_bf16_f32 v5, v90, v91
	global_load_dwordx2 v[90:91], v4, s[20:21] offset:1536
	v_cvt_pk_bf16_f32 v122, v26, v27
	v_lshlrev_b32_e32 v27, 16, v186
	v_lshlrev_b32_e32 v26, 16, v185
	s_waitcnt vmcnt(0)
	v_pk_mul_f32 v[94:95], v[90:91], v[26:27] op_sel:[0,1] op_sel_hi:[1,0]
	s_nop 0
	v_sub_f32_e32 v83, v94, v95
	v_pk_mul_f32 v[26:27], v[90:91], v[26:27]
	v_mul_f32_e32 v195, 0x3db504f3, v83
	v_add_f32_e32 v26, v26, v27
	v_mul_f32_e32 v83, 0x3db504f3, v26
	v_cvt_pk_bf16_f32 v26, v195, s0
	global_store_short v[120:121], v26, off offset:3264
	v_cvt_pk_bf16_f32 v26, v83, s0
	global_store_short v[120:121], v26, off offset:3392
	v_pk_mul_f32 v[26:27], v[2:3], v[194:195]
	v_pk_mul_f32 v[2:3], v[2:3], v[82:83]
	v_cvt_pk_bf16_f32 v90, v26, v27
	global_load_dwordx2 v[26:27], v4, s[20:21] offset:2048
	v_cvt_pk_bf16_f32 v91, v2, v3
	v_lshlrev_b32_e32 v3, 16, v184
	v_lshlrev_b32_e32 v2, 16, v183
	v_lshlrev_b32_e32 v95, 16, v182
	v_lshlrev_b32_e32 v94, 16, v181
	s_waitcnt vmcnt(0)
; DI bf16_t f2bf(float a) { return (bf16_t)(pack2(a, 0.f) & 0xffffu); }
; DI void post_z(const Params& p, int layer) {
;     ...
;       for (int i = 0; i < 32; ++i) {
;         bf16_t* p1 = zr + (size_t)i * ZS + colbase + lane;
;         float2 cs = rope[(spos + i) * 64 + lane];
;         float o1 = (x1[i] * cs.x - x2[i] * cs.y) * 0.08838834764831845f;
;         float o2 = (x1[i] * cs.y + x2[i] * cs.x) * 0.08838834764831845f;
;         p1[0] = f2bf(o1);
;         p1[64] = f2bf(o2);
	v_pk_mul_f32 v[82:83], v[26:27], v[2:3]
	s_nop 0
	v_sub_f32_e32 v82, v82, v83
	v_pk_mul_f32 v[2:3], v[26:27], v[2:3] op_sel:[0,1] op_sel_hi:[1,0]
	v_mul_f32_e32 v82, 0x3db504f3, v82
	v_add_f32_e32 v83, v2, v3
	v_and_b32_e32 v2, 0xffff0000, v90
	v_lshlrev_b32_e32 v3, 16, v90
	v_or_b32_sdwa v27, v2, v5 dst_sel:DWORD dst_unused:UNUSED_PAD src0_sel:DWORD src1_sel:WORD_1
	v_cvt_pk_bf16_f32 v2, v82, s0
	v_or_b32_sdwa v26, v3, v5 dst_sel:DWORD dst_unused:UNUSED_PAD src0_sel:DWORD src1_sel:WORD_0
	global_store_short v[118:119], v2, off offset:1776
	v_and_b32_e32 v2, 0xffff0000, v91
	v_lshlrev_b32_e32 v5, 16, v91
	v_mul_f32_e32 v90, 0x3db504f3, v83
	v_or_b32_sdwa v3, v2, v122 dst_sel:DWORD dst_unused:UNUSED_PAD src0_sel:DWORD src1_sel:WORD_1
	v_or_b32_sdwa v2, v5, v122 dst_sel:DWORD dst_unused:UNUSED_PAD src0_sel:DWORD src1_sel:WORD_0
	v_cvt_pk_bf16_f32 v5, v90, s0
	global_store_short v[118:119], v5, off offset:1904
	global_load_dwordx2 v[118:119], v4, s[20:21] offset:2560
	s_waitcnt vmcnt(0)
	v_pk_mul_f32 v[120:121], v[118:119], v[94:95] op_sel:[0,1] op_sel_hi:[1,0]
	s_nop 0
	v_sub_f32_e32 v5, v120, v121
	v_pk_mul_f32 v[94:95], v[118:119], v[94:95]
	global_load_dwordx2 v[118:119], v4, s[20:21] offset:3072
	v_mul_f32_e32 v120, 0x3db504f3, v5
	v_add_f32_e32 v5, v94, v95
	v_mul_f32_e32 v94, 0x3db504f3, v5
	v_cvt_pk_bf16_f32 v5, v120, s0
	global_store_short v[116:117], v5, off offset:288
	v_cvt_pk_bf16_f32 v5, v94, s0
	global_store_short v[116:117], v5, off offset:416
	v_lshlrev_b32_e32 v117, 16, v180
	v_lshlrev_b32_e32 v116, 16, v179
	s_waitcnt vmcnt(2)
	v_pk_mul_f32 v[122:123], v[118:119], v[116:117] op_sel:[0,1] op_sel_hi:[1,0]
	s_nop 0
	v_sub_f32_e32 v5, v122, v123
	v_pk_mul_f32 v[116:117], v[118:119], v[116:117]
	v_mul_f32_e32 v83, 0x3db504f3, v5
	v_add_f32_e32 v5, v116, v117
	v_mul_f32_e32 v91, 0x3db504f3, v5
	v_cvt_pk_bf16_f32 v5, v83, s0
	global_store_short v[114:115], v5, off offset:2896
	v_cvt_pk_bf16_f32 v5, v91, s0
	global_store_short v[114:115], v5, off offset:3024
	global_load_dwordx2 v[4:5], v4, s[20:21] offset:3584
	v_pk_mul_f32 v[82:83], v[68:69], v[82:83]
	v_pk_mul_f32 v[68:69], v[68:69], v[90:91]
	v_cvt_pk_bf16_f32 v114, v82, v83
	v_cvt_pk_bf16_f32 v115, v68, v69
	v_lshlrev_b32_e32 v69, 16, v178
	v_lshlrev_b32_e32 v68, 16, v177
	s_waitcnt vmcnt(0)
	v_pk_mul_f32 v[82:83], v[4:5], v[68:69] op_sel:[0,1] op_sel_hi:[1,0]
	s_nop 0
	v_sub_f32_e32 v82, v82, v83
	v_pk_mul_f32 v[4:5], v[4:5], v[68:69]
	v_mul_f32_e32 v121, 0x3db504f3, v82
	v_add_f32_e32 v4, v4, v5
	v_add_co_u32_e32 v82, vcc, s5, v16
	v_mul_f32_e32 v95, 0x3db504f3, v4
	v_cvt_pk_bf16_f32 v4, v121, s0
	v_addc_co_u32_e32 v83, vcc, 0, v17, vcc
	s_movk_i32 s5, 0x2000
	global_store_short v[112:113], v4, off offset:1408
	v_cvt_pk_bf16_f32 v4, v95, s0
	v_add_co_u32_e32 v68, vcc, s5, v16
	global_store_short v[112:113], v4, off offset:1536
	v_pk_mul_f32 v[4:5], v[28:29], v[120:121]
	v_addc_co_u32_e32 v69, vcc, 0, v17, vcc
	v_cvt_pk_bf16_f32 v112, v4, v5
	v_pk_mul_f32 v[4:5], v[28:29], v[94:95]
	global_load_dwordx2 v[28:29], v[68:69], off offset:-4096
	v_cvt_pk_bf16_f32 v94, v4, v5
	v_lshlrev_b32_e32 v5, 16, v176
	v_lshlrev_b32_e32 v4, 16, v175
	s_mov_b32 s5, 0x102000
	s_waitcnt vmcnt(0)
	v_pk_mul_f32 v[90:91], v[28:29], v[4:5]
	v_pk_mul_f32 v[4:5], v[28:29], v[4:5] op_sel:[0,1] op_sel_hi:[1,0]
	v_sub_f32_e32 v90, v90, v91
	v_add_f32_e32 v91, v4, v5
	v_and_b32_e32 v4, 0xffff0000, v112
	v_lshlrev_b32_e32 v5, 16, v112
	v_or_b32_sdwa v29, v4, v114 dst_sel:DWORD dst_unused:UNUSED_PAD src0_sel:DWORD src1_sel:WORD_1
	v_and_b32_e32 v4, 0xffff0000, v94
	v_lshlrev_b32_e32 v94, 16, v94
	v_mul_f32_e32 v90, 0x3db504f3, v90
	v_or_b32_sdwa v28, v5, v114 dst_sel:DWORD dst_unused:UNUSED_PAD src0_sel:DWORD src1_sel:WORD_0
	v_or_b32_sdwa v5, v4, v115 dst_sel:DWORD dst_unused:UNUSED_PAD src0_sel:DWORD src1_sel:WORD_1
	v_or_b32_sdwa v4, v94, v115 dst_sel:DWORD dst_unused:UNUSED_PAD src0_sel:DWORD src1_sel:WORD_0
	v_cvt_pk_bf16_f32 v94, v90, s0
	global_store_short v[110:111], v94, off offset:4016
	global_load_dwordx2 v[110:111], v[82:83], off offset:512
	v_mul_f32_e32 v94, 0x3db504f3, v91
	v_cvt_pk_bf16_f32 v91, v94, s0
	global_store_short v[108:109], v91, off offset:48
	v_lshlrev_b32_e32 v109, 16, v173
	v_lshlrev_b32_e32 v108, 16, v172
	s_waitcnt vmcnt(1)
	v_pk_mul_f32 v[112:113], v[110:111], v[108:109] op_sel:[0,1] op_sel_hi:[1,0]
	s_nop 0
	v_sub_f32_e32 v91, v112, v113
	v_pk_mul_f32 v[108:109], v[110:111], v[108:109]
	global_load_dwordx2 v[110:111], v[82:83], off offset:1024
	v_mul_f32_e32 v112, 0x3db504f3, v91
	v_add_f32_e32 v91, v108, v109
	v_mul_f32_e32 v108, 0x3db504f3, v91
	v_cvt_pk_bf16_f32 v91, v112, s0
	global_store_short v[106:107], v91, off offset:2528
	v_cvt_pk_bf16_f32 v91, v108, s0
	global_store_short v[106:107], v91, off offset:2656
	v_lshlrev_b32_e32 v107, 16, v171
	v_lshlrev_b32_e32 v106, 16, v170
	s_waitcnt vmcnt(2)
	v_pk_mul_f32 v[114:115], v[110:111], v[106:107] op_sel:[0,1] op_sel_hi:[1,0]
	s_nop 0
	v_sub_f32_e32 v91, v114, v115
	v_pk_mul_f32 v[106:107], v[110:111], v[106:107]
	v_mul_f32_e32 v91, 0x3db504f3, v91
	v_add_f32_e32 v95, v106, v107
	v_mul_f32_e32 v95, 0x3db504f3, v95
	v_cvt_pk_bf16_f32 v106, v91, s0
	global_store_short v[104:105], v106, off offset:1040
	v_cvt_pk_bf16_f32 v106, v95, s0
	global_store_short v[104:105], v106, off offset:1168
	v_pk_mul_f32 v[90:91], v[10:11], v[90:91]
	v_pk_mul_f32 v[10:11], v[10:11], v[94:95]
	v_cvt_pk_bf16_f32 v104, v90, v91
	global_load_dwordx2 v[90:91], v[82:83], off offset:1536
	v_cvt_pk_bf16_f32 v105, v10, v11
	v_lshlrev_b32_e32 v11, 16, v169
	v_lshlrev_b32_e32 v10, 16, v168
	s_waitcnt vmcnt(0)
; DI bf16_t f2bf(float a) { return (bf16_t)(pack2(a, 0.f) & 0xffffu); }
; DI void post_z(const Params& p, int layer) {
;     ...
;       for (int i = 0; i < 32; ++i) {
;         bf16_t* p1 = zr + (size_t)i * ZS + colbase + lane;
;         float2 cs = rope[(spos + i) * 64 + lane];
;         float o1 = (x1[i] * cs.x - x2[i] * cs.y) * 0.08838834764831845f;
;         float o2 = (x1[i] * cs.y + x2[i] * cs.x) * 0.08838834764831845f;
;         p1[0] = f2bf(o1);
;         p1[64] = f2bf(o2);
	v_pk_mul_f32 v[94:95], v[90:91], v[10:11] op_sel:[0,1] op_sel_hi:[1,0]
	s_nop 0
	v_sub_f32_e32 v94, v94, v95
	v_pk_mul_f32 v[10:11], v[90:91], v[10:11]
	v_mul_f32_e32 v113, 0x3db504f3, v94
	v_add_f32_e32 v10, v10, v11
	v_mul_f32_e32 v109, 0x3db504f3, v10
	v_cvt_pk_bf16_f32 v10, v113, s0
	global_store_short v[102:103], v10, off offset:3648
	v_cvt_pk_bf16_f32 v10, v109, s0
	global_store_short v[102:103], v10, off offset:3776
	v_pk_mul_f32 v[10:11], v[6:7], v[112:113]
	v_pk_mul_f32 v[6:7], v[6:7], v[108:109]
	v_cvt_pk_bf16_f32 v94, v10, v11
	global_load_dwordx2 v[10:11], v[82:83], off offset:2048
	v_cvt_pk_bf16_f32 v95, v6, v7
	v_lshlrev_b32_e32 v7, 16, v167
	v_lshlrev_b32_e32 v6, 16, v166
	s_waitcnt vmcnt(0)
	global_load_dwordx2 v[102:103], v[82:83], off offset:2560
	v_pk_mul_f32 v[90:91], v[10:11], v[6:7]
	s_nop 0
	v_sub_f32_e32 v90, v90, v91
	v_pk_mul_f32 v[6:7], v[10:11], v[6:7] op_sel:[0,1] op_sel_hi:[1,0]
	v_lshlrev_b32_e32 v10, 16, v94
	v_add_f32_e32 v91, v6, v7
	v_and_b32_e32 v6, 0xffff0000, v94
	v_mul_f32_e32 v90, 0x3db504f3, v90
	v_or_b32_sdwa v7, v6, v104 dst_sel:DWORD dst_unused:UNUSED_PAD src0_sel:DWORD src1_sel:WORD_1
	v_or_b32_sdwa v6, v10, v104 dst_sel:DWORD dst_unused:UNUSED_PAD src0_sel:DWORD src1_sel:WORD_0
	v_cvt_pk_bf16_f32 v10, v90, s0
	global_store_short v[100:101], v10, off offset:2160
	v_and_b32_e32 v10, 0xffff0000, v95
	v_lshlrev_b32_e32 v94, 16, v95
	v_or_b32_sdwa v11, v10, v105 dst_sel:DWORD dst_unused:UNUSED_PAD src0_sel:DWORD src1_sel:WORD_1
	v_or_b32_sdwa v10, v94, v105 dst_sel:DWORD dst_unused:UNUSED_PAD src0_sel:DWORD src1_sel:WORD_0
	v_mul_f32_e32 v94, 0x3db504f3, v91
	v_cvt_pk_bf16_f32 v91, v94, s0
	global_store_short v[100:101], v91, off offset:2288
	v_lshlrev_b32_e32 v101, 16, v165
	v_lshlrev_b32_e32 v100, 16, v164
	s_waitcnt vmcnt(2)
	v_pk_mul_f32 v[104:105], v[102:103], v[100:101] op_sel:[0,1] op_sel_hi:[1,0]
	s_nop 0
	v_sub_f32_e32 v91, v104, v105
	v_pk_mul_f32 v[100:101], v[102:103], v[100:101]
	global_load_dwordx2 v[102:103], v[82:83], off offset:3072
	v_mul_f32_e32 v104, 0x3db504f3, v91
	v_add_f32_e32 v91, v100, v101
	v_mul_f32_e32 v100, 0x3db504f3, v91
	v_cvt_pk_bf16_f32 v91, v104, s0
	global_store_short v[98:99], v91, off offset:672
	v_cvt_pk_bf16_f32 v91, v100, s0
	global_store_short v[98:99], v91, off offset:800
	v_lshlrev_b32_e32 v99, 16, v163
	v_lshlrev_b32_e32 v98, 16, v161
	s_waitcnt vmcnt(2)
	global_load_dwordx2 v[82:83], v[82:83], off offset:3584
	v_pk_mul_f32 v[106:107], v[102:103], v[98:99] op_sel:[0,1] op_sel_hi:[1,0]
	s_nop 0
	v_sub_f32_e32 v91, v106, v107
	v_pk_mul_f32 v[98:99], v[102:103], v[98:99]
	v_mul_f32_e32 v91, 0x3db504f3, v91
	v_add_f32_e32 v95, v98, v99
	v_mul_f32_e32 v95, 0x3db504f3, v95
	v_cvt_pk_bf16_f32 v98, v91, s0
	global_store_short v[96:97], v98, off offset:3280
	v_cvt_pk_bf16_f32 v98, v95, s0
	global_store_short v[96:97], v98, off offset:3408
	v_pk_mul_f32 v[90:91], v[12:13], v[90:91]
	v_pk_mul_f32 v[12:13], v[12:13], v[94:95]
	v_cvt_pk_bf16_f32 v96, v90, v91
	v_cvt_pk_bf16_f32 v94, v12, v13
	v_lshlrev_b32_e32 v13, 16, v160
	v_lshlrev_b32_e32 v12, 16, v159
	s_waitcnt vmcnt(2)
	v_pk_mul_f32 v[90:91], v[82:83], v[12:13] op_sel:[0,1] op_sel_hi:[1,0]
	s_nop 0
	v_sub_f32_e32 v90, v90, v91
	v_pk_mul_f32 v[12:13], v[82:83], v[12:13]
	v_mul_f32_e32 v105, 0x3db504f3, v90
	v_add_f32_e32 v12, v12, v13
	v_mul_f32_e32 v101, 0x3db504f3, v12
	v_cvt_pk_bf16_f32 v12, v105, s0
	global_store_short v[92:93], v12, off offset:1792
	v_cvt_pk_bf16_f32 v12, v101, s0
	global_store_short v[92:93], v12, off offset:1920
	v_pk_mul_f32 v[12:13], v[8:9], v[104:105]
	v_pk_mul_f32 v[8:9], v[8:9], v[100:101]
	v_cvt_pk_bf16_f32 v90, v12, v13
	global_load_dwordx2 v[12:13], v[68:69], off
	v_cvt_pk_bf16_f32 v91, v8, v9
	v_lshlrev_b32_e32 v9, 16, v157
	v_lshlrev_b32_e32 v8, 16, v156
	s_waitcnt vmcnt(0)
	global_load_dwordx2 v[92:93], v[68:69], off offset:512
	v_pk_mul_f32 v[82:83], v[12:13], v[8:9]
	v_pk_mul_f32 v[8:9], v[12:13], v[8:9] op_sel:[0,1] op_sel_hi:[1,0]
	v_sub_f32_e32 v82, v82, v83
	v_add_f32_e32 v83, v8, v9
	v_and_b32_e32 v8, 0xffff0000, v90
	v_lshlrev_b32_e32 v12, 16, v90
	v_or_b32_sdwa v9, v8, v96 dst_sel:DWORD dst_unused:UNUSED_PAD src0_sel:DWORD src1_sel:WORD_1
	v_or_b32_sdwa v8, v12, v96 dst_sel:DWORD dst_unused:UNUSED_PAD src0_sel:DWORD src1_sel:WORD_0
	v_and_b32_e32 v12, 0xffff0000, v91
	v_lshlrev_b32_e32 v90, 16, v91
	v_mul_f32_e32 v82, 0x3db504f3, v82
	v_or_b32_sdwa v13, v12, v94 dst_sel:DWORD dst_unused:UNUSED_PAD src0_sel:DWORD src1_sel:WORD_1
	v_or_b32_sdwa v12, v90, v94 dst_sel:DWORD dst_unused:UNUSED_PAD src0_sel:DWORD src1_sel:WORD_0
	v_cvt_pk_bf16_f32 v90, v82, s0
	global_store_short v[88:89], v90, off offset:304
	v_mul_f32_e32 v90, 0x3db504f3, v83
	v_cvt_pk_bf16_f32 v83, v90, s0
	global_store_short v[88:89], v83, off offset:432
	v_lshlrev_b32_e32 v89, 16, v155
	v_lshlrev_b32_e32 v88, 16, v154
	s_waitcnt vmcnt(2)
	v_pk_mul_f32 v[94:95], v[92:93], v[88:89] op_sel:[0,1] op_sel_hi:[1,0]
	s_nop 0
	v_sub_f32_e32 v83, v94, v95
	v_pk_mul_f32 v[88:89], v[92:93], v[88:89]
	global_load_dwordx2 v[92:93], v[68:69], off offset:1024
	v_mul_f32_e32 v94, 0x3db504f3, v83
	v_add_f32_e32 v83, v88, v89
	v_mul_f32_e32 v88, 0x3db504f3, v83
	v_cvt_pk_bf16_f32 v83, v94, s0
	global_store_short v[86:87], v83, off offset:2912
	v_cvt_pk_bf16_f32 v83, v88, s0
	global_store_short v[86:87], v83, off offset:3040
	v_lshlrev_b32_e32 v87, 16, v153
	v_lshlrev_b32_e32 v86, 16, v152
	s_waitcnt vmcnt(2)
; DI bf16_t f2bf(float a) { return (bf16_t)(pack2(a, 0.f) & 0xffffu); }
; DI void post_z(const Params& p, int layer) {
;     ...
;       for (int i = 0; i < 32; ++i) {
;         bf16_t* p1 = zr + (size_t)i * ZS + colbase + lane;
;         float2 cs = rope[(spos + i) * 64 + lane];
;         float o1 = (x1[i] * cs.x - x2[i] * cs.y) * 0.08838834764831845f;
;         float o2 = (x1[i] * cs.y + x2[i] * cs.x) * 0.08838834764831845f;
;         p1[0] = f2bf(o1);
;         p1[64] = f2bf(o2);
	v_pk_mul_f32 v[96:97], v[92:93], v[86:87] op_sel:[0,1] op_sel_hi:[1,0]
	s_nop 0
	v_sub_f32_e32 v83, v96, v97
	v_pk_mul_f32 v[86:87], v[92:93], v[86:87]
	v_mul_f32_e32 v83, 0x3db504f3, v83
	v_add_f32_e32 v86, v86, v87
	v_mul_f32_e32 v91, 0x3db504f3, v86
	v_cvt_pk_bf16_f32 v86, v83, s0
	global_store_short v[84:85], v86, off offset:1424
	v_cvt_pk_bf16_f32 v86, v91, s0
	global_store_short v[84:85], v86, off offset:1552
	v_pk_mul_f32 v[82:83], v[18:19], v[82:83]
	v_pk_mul_f32 v[18:19], v[18:19], v[90:91]
	v_cvt_pk_bf16_f32 v86, v82, v83
	global_load_dwordx2 v[82:83], v[68:69], off offset:1536
	v_cvt_pk_bf16_f32 v87, v18, v19
	v_lshlrev_b32_e32 v19, 16, v151
	v_lshlrev_b32_e32 v18, 16, v150
	s_waitcnt vmcnt(0)
	v_pk_mul_f32 v[84:85], v[82:83], v[18:19] op_sel:[0,1] op_sel_hi:[1,0]
	s_nop 0
	v_sub_f32_e32 v84, v84, v85
	v_pk_mul_f32 v[18:19], v[82:83], v[18:19]
	v_mul_f32_e32 v95, 0x3db504f3, v84
	v_add_f32_e32 v18, v18, v19
	v_mul_f32_e32 v89, 0x3db504f3, v18
	v_cvt_pk_bf16_f32 v18, v95, s0
	global_store_short v[80:81], v18, off offset:4032
	v_cvt_pk_bf16_f32 v18, v89, s0
	global_store_short v[78:79], v18, off offset:64
	v_pk_mul_f32 v[18:19], v[14:15], v[94:95]
	v_pk_mul_f32 v[14:15], v[14:15], v[88:89]
	v_cvt_pk_bf16_f32 v80, v18, v19
	global_load_dwordx2 v[18:19], v[68:69], off offset:2048
	v_cvt_pk_bf16_f32 v81, v14, v15
	v_lshlrev_b32_e32 v15, 16, v149
	v_lshlrev_b32_e32 v14, 16, v148
	s_waitcnt vmcnt(0)
	global_load_dwordx2 v[82:83], v[68:69], off offset:2560
	v_pk_mul_f32 v[78:79], v[18:19], v[14:15]
	s_nop 0
	v_sub_f32_e32 v78, v78, v79
	v_pk_mul_f32 v[14:15], v[18:19], v[14:15] op_sel:[0,1] op_sel_hi:[1,0]
	v_lshlrev_b32_e32 v18, 16, v80
	v_add_f32_e32 v79, v14, v15
	v_and_b32_e32 v14, 0xffff0000, v80
	v_mul_f32_e32 v78, 0x3db504f3, v78
	v_or_b32_sdwa v15, v14, v86 dst_sel:DWORD dst_unused:UNUSED_PAD src0_sel:DWORD src1_sel:WORD_1
	v_or_b32_sdwa v14, v18, v86 dst_sel:DWORD dst_unused:UNUSED_PAD src0_sel:DWORD src1_sel:WORD_0
	v_cvt_pk_bf16_f32 v18, v78, s0
	global_store_short v[76:77], v18, off offset:2544
	v_and_b32_e32 v18, 0xffff0000, v81
	v_lshlrev_b32_e32 v80, 16, v81
	v_or_b32_sdwa v19, v18, v87 dst_sel:DWORD dst_unused:UNUSED_PAD src0_sel:DWORD src1_sel:WORD_1
	v_or_b32_sdwa v18, v80, v87 dst_sel:DWORD dst_unused:UNUSED_PAD src0_sel:DWORD src1_sel:WORD_0
	v_mul_f32_e32 v80, 0x3db504f3, v79
	v_cvt_pk_bf16_f32 v79, v80, s0
	global_store_short v[76:77], v79, off offset:2672
	v_lshlrev_b32_e32 v77, 16, v147
	v_lshlrev_b32_e32 v76, 16, v146
	s_waitcnt vmcnt(2)
	v_pk_mul_f32 v[84:85], v[82:83], v[76:77] op_sel:[0,1] op_sel_hi:[1,0]
	s_nop 0
	v_sub_f32_e32 v79, v84, v85
	v_pk_mul_f32 v[76:77], v[82:83], v[76:77]
	global_load_dwordx2 v[82:83], v[68:69], off offset:3072
	v_mul_f32_e32 v84, 0x3db504f3, v79
	v_add_f32_e32 v76, v76, v77
	v_mul_f32_e32 v76, 0x3db504f3, v76
	v_cvt_pk_bf16_f32 v77, v84, s0
	global_store_short v[74:75], v77, off offset:1056
	v_cvt_pk_bf16_f32 v77, v76, s0
	global_store_short v[74:75], v77, off offset:1184
	v_lshlrev_b32_e32 v75, 16, v145
	v_lshlrev_b32_e32 v74, 16, v144
	s_waitcnt vmcnt(2)
	global_load_dwordx2 v[68:69], v[68:69], off offset:3584
	v_pk_mul_f32 v[86:87], v[82:83], v[74:75] op_sel:[0,1] op_sel_hi:[1,0]
	s_nop 0
	v_sub_f32_e32 v77, v86, v87
	v_pk_mul_f32 v[74:75], v[82:83], v[74:75]
	v_mul_f32_e32 v79, 0x3db504f3, v77
	v_add_f32_e32 v74, v74, v75
	v_mul_f32_e32 v81, 0x3db504f3, v74
	v_cvt_pk_bf16_f32 v74, v79, s0
	global_store_short v[72:73], v74, off offset:3664
	v_cvt_pk_bf16_f32 v74, v81, s0
	global_store_short v[72:73], v74, off offset:3792
	v_pk_mul_f32 v[72:73], v[48:49], v[78:79]
	v_pk_mul_f32 v[48:49], v[48:49], v[80:81]
	v_cvt_pk_bf16_f32 v74, v72, v73
	v_cvt_pk_bf16_f32 v75, v48, v49
	v_lshlrev_b32_e32 v49, 16, v143
	v_lshlrev_b32_e32 v48, 16, v142
	s_waitcnt vmcnt(2)
	v_pk_mul_f32 v[72:73], v[68:69], v[48:49] op_sel:[0,1] op_sel_hi:[1,0]
	s_nop 0
	v_sub_f32_e32 v72, v72, v73
	v_pk_mul_f32 v[48:49], v[68:69], v[48:49]
	v_mul_f32_e32 v85, 0x3db504f3, v72
	v_add_f32_e32 v48, v48, v49
	v_mul_f32_e32 v77, 0x3db504f3, v48
	v_cvt_pk_bf16_f32 v48, v85, s0
	global_store_short v[70:71], v48, off offset:2176
	v_cvt_pk_bf16_f32 v48, v77, s0
	global_store_short v[70:71], v48, off offset:2304
	v_pk_mul_f32 v[48:49], v[20:21], v[84:85]
	v_pk_mul_f32 v[20:21], v[20:21], v[76:77]
	v_cvt_pk_bf16_f32 v70, v48, v49
	v_add_co_u32_e32 v48, vcc, s12, v16
	v_cvt_pk_bf16_f32 v71, v20, v21
	s_nop 0
	v_addc_co_u32_e32 v49, vcc, 0, v17, vcc
	global_load_dwordx2 v[16:17], v[48:49], off
	v_lshlrev_b32_e32 v21, 16, v141
	v_lshlrev_b32_e32 v20, 16, v140
	s_waitcnt vmcnt(0)
	global_load_dwordx2 v[72:73], v[48:49], off offset:512
	v_pk_mul_f32 v[68:69], v[16:17], v[20:21]
	v_pk_mul_f32 v[16:17], v[16:17], v[20:21] op_sel:[0,1] op_sel_hi:[1,0]
	v_sub_f32_e32 v68, v68, v69
	v_add_f32_e32 v69, v16, v17
	v_and_b32_e32 v16, 0xffff0000, v70
	v_lshlrev_b32_e32 v20, 16, v70
	v_or_b32_sdwa v17, v16, v74 dst_sel:DWORD dst_unused:UNUSED_PAD src0_sel:DWORD src1_sel:WORD_1
	v_or_b32_sdwa v16, v20, v74 dst_sel:DWORD dst_unused:UNUSED_PAD src0_sel:DWORD src1_sel:WORD_0
	v_and_b32_e32 v20, 0xffff0000, v71
	v_lshlrev_b32_e32 v70, 16, v71
	v_mul_f32_e32 v68, 0x3db504f3, v68
	v_or_b32_sdwa v21, v20, v75 dst_sel:DWORD dst_unused:UNUSED_PAD src0_sel:DWORD src1_sel:WORD_1
	v_or_b32_sdwa v20, v70, v75 dst_sel:DWORD dst_unused:UNUSED_PAD src0_sel:DWORD src1_sel:WORD_0
	v_cvt_pk_bf16_f32 v70, v68, s0
	global_store_short v[66:67], v70, off offset:688
	v_mul_f32_e32 v70, 0x3db504f3, v69
	v_cvt_pk_bf16_f32 v69, v70, s0
	global_store_short v[66:67], v69, off offset:816
	v_lshlrev_b32_e32 v67, 16, v139
	v_lshlrev_b32_e32 v66, 16, v138
	s_waitcnt vmcnt(2)
; DI bf16_t f2bf(float a) { return (bf16_t)(pack2(a, 0.f) & 0xffffu); }
; DI void post_z(const Params& p, int layer) {
;     ...
;       for (int i = 0; i < 32; ++i) {
;         bf16_t* p1 = zr + (size_t)i * ZS + colbase + lane;
;         float2 cs = rope[(spos + i) * 64 + lane];
;         float o1 = (x1[i] * cs.x - x2[i] * cs.y) * 0.08838834764831845f;
;         float o2 = (x1[i] * cs.y + x2[i] * cs.x) * 0.08838834764831845f;
;         p1[0] = f2bf(o1);
;         p1[64] = f2bf(o2);
;         float zeta = exp2f(lg2 * (float)(127 - ((spos + i) & 127)));
;         u1[i] = f2bf(o1 * zeta);
;         u2[i] = f2bf(o2 * zeta);
;       }
;       bf16_t* d1 = kzT + ((size_t)((b * 4 + h) * 128 + lane)) * TS + spos;
; #pragma unroll
;       for (int q4 = 0; q4 < 4; ++q4) {
;         *(uint4*)(d1 + q4 * 8) = make_uint4(u1[q4 * 8 + 0] | (u1[q4 * 8 + 1] << 16), u1[q4 * 8 + 2] | (u1[q4 * 8 + 3] << 16),
;                                             u1[q4 * 8 + 4] | (u1[q4 * 8 + 5] << 16), u1[q4 * 8 + 6] | (u1[q4 * 8 + 7] << 16));
;         *(uint4*)(d1 + (size_t)64 * TS + q4 * 8) = make_uint4(u2[q4 * 8 + 0] | (u2[q4 * 8 + 1] << 16), u2[q4 * 8 + 2] | (u2[q4 * 8 + 3] << 16),
;                                                               u2[q4 * 8 + 4] | (u2[q4 * 8 + 5] << 16), u2[q4 * 8 + 6] | (u2[q4 * 8 + 7] << 16));
;       }
	v_pk_mul_f32 v[74:75], v[72:73], v[66:67] op_sel:[0,1] op_sel_hi:[1,0]
	s_nop 0
	v_sub_f32_e32 v69, v74, v75
	v_pk_mul_f32 v[66:67], v[72:73], v[66:67]
	global_load_dwordx2 v[72:73], v[48:49], off offset:1024
	v_mul_f32_e32 v74, 0x3db504f3, v69
	v_add_f32_e32 v66, v66, v67
	v_mul_f32_e32 v66, 0x3db504f3, v66
	v_cvt_pk_bf16_f32 v67, v74, s0
	global_store_short v[64:65], v67, off offset:3296
	v_cvt_pk_bf16_f32 v67, v66, s0
	global_store_short v[64:65], v67, off offset:3424
	v_lshlrev_b32_e32 v65, 16, v137
	v_lshlrev_b32_e32 v64, 16, v136
	s_waitcnt vmcnt(2)
	v_pk_mul_f32 v[76:77], v[72:73], v[64:65] op_sel:[0,1] op_sel_hi:[1,0]
	s_nop 0
	v_sub_f32_e32 v67, v76, v77
	v_pk_mul_f32 v[64:65], v[72:73], v[64:65]
	v_mul_f32_e32 v69, 0x3db504f3, v67
	v_add_f32_e32 v64, v64, v65
	v_mul_f32_e32 v71, 0x3db504f3, v64
	v_cvt_pk_bf16_f32 v64, v69, s0
	global_store_short v[62:63], v64, off offset:1808
	v_cvt_pk_bf16_f32 v64, v71, s0
	global_store_short v[62:63], v64, off offset:1936
	v_pk_mul_f32 v[62:63], v[24:25], v[68:69]
	v_pk_mul_f32 v[24:25], v[24:25], v[70:71]
	v_cvt_pk_bf16_f32 v68, v62, v63
	global_load_dwordx2 v[62:63], v[48:49], off offset:1536
	v_cvt_pk_bf16_f32 v69, v24, v25
	v_lshlrev_b32_e32 v25, 16, v135
	v_lshlrev_b32_e32 v24, 16, v134
	s_waitcnt vmcnt(0)
	v_pk_mul_f32 v[64:65], v[62:63], v[24:25] op_sel:[0,1] op_sel_hi:[1,0]
	s_nop 0
	v_sub_f32_e32 v64, v64, v65
	v_pk_mul_f32 v[24:25], v[62:63], v[24:25]
	v_mul_f32_e32 v75, 0x3db504f3, v64
	v_add_f32_e32 v24, v24, v25
	v_mul_f32_e32 v67, 0x3db504f3, v24
	v_cvt_pk_bf16_f32 v24, v75, s0
	global_store_short v[60:61], v24, off offset:320
	v_cvt_pk_bf16_f32 v24, v67, s0
	global_store_short v[60:61], v24, off offset:448
	v_pk_mul_f32 v[24:25], v[22:23], v[74:75]
	v_pk_mul_f32 v[22:23], v[22:23], v[66:67]
	v_cvt_pk_bf16_f32 v62, v24, v25
	global_load_dwordx2 v[24:25], v[48:49], off offset:2048
	v_cvt_pk_bf16_f32 v63, v22, v23
	v_lshlrev_b32_e32 v23, 16, v133
	v_lshlrev_b32_e32 v22, 16, v132
	s_waitcnt vmcnt(0)
	global_load_dwordx2 v[64:65], v[48:49], off offset:2560
	v_pk_mul_f32 v[60:61], v[24:25], v[22:23]
	s_nop 0
	v_sub_f32_e32 v60, v60, v61
	v_pk_mul_f32 v[22:23], v[24:25], v[22:23] op_sel:[0,1] op_sel_hi:[1,0]
	v_mul_f32_e32 v60, 0x3db504f3, v60
	v_add_f32_e32 v61, v22, v23
	v_and_b32_e32 v22, 0xffff0000, v62
	v_or_b32_sdwa v25, v22, v68 dst_sel:DWORD dst_unused:UNUSED_PAD src0_sel:DWORD src1_sel:WORD_1
	v_cvt_pk_bf16_f32 v22, v60, s0
	v_lshlrev_b32_e32 v23, 16, v62
	global_store_short v[58:59], v22, off offset:2928
	v_and_b32_e32 v22, 0xffff0000, v63
	v_lshlrev_b32_e32 v62, 16, v63
	v_or_b32_sdwa v24, v23, v68 dst_sel:DWORD dst_unused:UNUSED_PAD src0_sel:DWORD src1_sel:WORD_0
	v_or_b32_sdwa v23, v22, v69 dst_sel:DWORD dst_unused:UNUSED_PAD src0_sel:DWORD src1_sel:WORD_1
	v_or_b32_sdwa v22, v62, v69 dst_sel:DWORD dst_unused:UNUSED_PAD src0_sel:DWORD src1_sel:WORD_0
	v_mul_f32_e32 v62, 0x3db504f3, v61
	v_cvt_pk_bf16_f32 v61, v62, s0
	global_store_short v[58:59], v61, off offset:3056
	v_lshlrev_b32_e32 v59, 16, v131
	v_lshlrev_b32_e32 v58, 16, v130
	s_waitcnt vmcnt(2)
	v_pk_mul_f32 v[66:67], v[64:65], v[58:59] op_sel:[0,1] op_sel_hi:[1,0]
	s_nop 0
	v_sub_f32_e32 v61, v66, v67
	v_pk_mul_f32 v[58:59], v[64:65], v[58:59]
	global_load_dwordx2 v[64:65], v[48:49], off offset:3072
	v_mul_f32_e32 v66, 0x3db504f3, v61
	v_add_f32_e32 v58, v58, v59
	v_mul_f32_e32 v58, 0x3db504f3, v58
	v_cvt_pk_bf16_f32 v59, v66, s0
	global_store_short v[56:57], v59, off offset:1440
	v_cvt_pk_bf16_f32 v59, v58, s0
	global_store_short v[56:57], v59, off offset:1568
	v_lshlrev_b32_e32 v57, 16, v129
	v_lshlrev_b32_e32 v56, 16, v128
	s_waitcnt vmcnt(2)
	global_load_dwordx2 v[48:49], v[48:49], off offset:3584
	v_pk_mul_f32 v[68:69], v[64:65], v[56:57] op_sel:[0,1] op_sel_hi:[1,0]
	s_nop 0
	v_sub_f32_e32 v59, v68, v69
	v_pk_mul_f32 v[56:57], v[64:65], v[56:57]
	v_mul_f32_e32 v61, 0x3db504f3, v59
	v_add_f32_e32 v56, v56, v57
	v_mul_f32_e32 v63, 0x3db504f3, v56
	v_cvt_pk_bf16_f32 v56, v61, s0
	global_store_short v[54:55], v56, off offset:4048
	v_cvt_pk_bf16_f32 v54, v63, s0
	global_store_short v[52:53], v54, off offset:80
	v_lshlrev_b32_e32 v55, 16, v127
	v_lshlrev_b32_e32 v54, 16, v0
	v_pk_mul_f32 v[52:53], v[46:47], v[60:61]
	v_pk_mul_f32 v[46:47], v[46:47], v[62:63]
	v_cvt_pk_bf16_f32 v52, v52, v53
	v_cvt_pk_bf16_f32 v46, v46, v47
	s_waitcnt vmcnt(2)
	v_pk_mul_f32 v[56:57], v[48:49], v[54:55] op_sel:[0,1] op_sel_hi:[1,0]
	s_nop 0
	v_sub_f32_e32 v0, v56, v57
	v_pk_mul_f32 v[48:49], v[48:49], v[54:55]
	v_mul_f32_e32 v67, 0x3db504f3, v0
	v_add_f32_e32 v0, v48, v49
	v_mul_f32_e32 v59, 0x3db504f3, v0
	v_cvt_pk_bf16_f32 v0, v67, s0
	global_store_short v[50:51], v0, off offset:2560
	v_cvt_pk_bf16_f32 v0, v59, s0
	global_store_short v[50:51], v0, off offset:2688
	v_pk_mul_f32 v[48:49], v[44:45], v[66:67]
	global_store_dwordx4 v[42:43], v[26:29], off
	v_cvt_pk_bf16_f32 v47, v48, v49
	v_pk_mul_f32 v[44:45], v[44:45], v[58:59]
	v_add_co_u32_e32 v28, vcc, s5, v42
	v_cvt_pk_bf16_f32 v0, v44, v45
	s_nop 0
	v_addc_co_u32_e32 v29, vcc, 0, v43, vcc
	global_store_dwordx4 v[28:29], v[2:5], off
	global_store_dwordx4 v[42:43], v[6:9], off offset:16
	global_store_dwordx4 v[28:29], v[10:13], off offset:16
	global_store_dwordx4 v[42:43], v[14:17], off offset:32
	global_store_dwordx4 v[28:29], v[18:21], off offset:32
	v_and_b32_e32 v2, 0xffff0000, v47
	v_lshlrev_b32_e32 v3, 16, v47
	v_or_b32_sdwa v27, v2, v52 dst_sel:DWORD dst_unused:UNUSED_PAD src0_sel:DWORD src1_sel:WORD_1
	v_or_b32_sdwa v26, v3, v52 dst_sel:DWORD dst_unused:UNUSED_PAD src0_sel:DWORD src1_sel:WORD_0
	v_and_b32_e32 v2, 0xffff0000, v0
	v_lshlrev_b32_e32 v0, 16, v0
	global_store_dwordx4 v[42:43], v[24:27], off offset:48
	s_nop 1
	v_or_b32_sdwa v25, v2, v46 dst_sel:DWORD dst_unused:UNUSED_PAD src0_sel:DWORD src1_sel:WORD_1
	v_or_b32_sdwa v24, v0, v46 dst_sel:DWORD dst_unused:UNUSED_PAD src0_sel:DWORD src1_sel:WORD_0
	global_store_dwordx4 v[28:29], v[22:25], off offset:48

; DI float bflo(unsigned u) { return __uint_as_float(u << 16); }
; DI float bfhi(unsigned u) { return __uint_as_float(u & 0xffff0000u); }
; DI void phase4b(const Params& p, int layer) {
;     ...
;   for (int item = gw; item < 8192; item += nw) {
;     const int kv = item >> 12, row = item & 4095;
;     const bf16_t* hrow = hid + ((size_t)kv * 4096 + row) * 256;
;     const float* w2 = (kv ? p.cmp_w2_v : p.cmp_w2_k) + (size_t)layer * 256 * 64;
;     float acc = 0.f;
;     for (int k8 = 0; k8 < 32; ++k8) {
;       uint4 hv = *(const uint4*)(hrow + k8 * 8);
;       const float* wr = w2 + (size_t)(k8 * 8) * 64 + lane;
;       acc += bflo(hv.x) * wr[0];
;       acc += bfhi(hv.x) * wr[64];
;       acc += bflo(hv.y) * wr[128];
;       acc += bfhi(hv.y) * wr[192];
;       acc += bflo(hv.z) * wr[256];
;       acc += bfhi(hv.z) * wr[320];
;       acc += bflo(hv.w) * wr[384];
;       acc += bfhi(hv.w) * wr[448];
;     }
.LBB0_305:
	v_ashrrev_i32_e32 v8, 12, v14
	s_movk_i32 s2, 0xfff
	v_readlane_b32 s36, v251, 17
	v_ashrrev_i32_e32 v9, 31, v8
	v_cmp_lt_u32_e32 vcc, s2, v14
	v_readlane_b32 s39, v251, 20
	v_readlane_b32 s43, v251, 24
	s_movk_i32 s2, 0x1000
	v_lshlrev_b64 v[10:11], 21, v[8:9]
	v_readlane_b32 s38, v251, 19
	v_readlane_b32 s42, v251, 23
	v_mov_b32_e32 v8, s43
	v_mov_b32_e32 v9, s39
	v_cmp_gt_u32_e64 s[2:3], s2, v14
	v_mov_b32_e32 v13, s38
	v_and_b32_e32 v12, 0xfff, v15
	v_cndmask_b32_e64 v9, v8, v9, s[2:3]
	v_mov_b32_e32 v8, s42
	v_cndmask_b32_e64 v8, v8, v13, s[2:3]
	v_readlane_b32 s2, v253, 61
	v_lshl_add_u64 v[8:9], s[28:29], 2, v[8:9]
	v_lshl_or_b32 v10, v12, 9, v10
	v_readlane_b32 s3, v253, 62
	v_lshl_add_u64 v[8:9], v[8:9], 0, v[0:1]
	v_mov_b32_e32 v22, 0
	v_lshl_add_u64 v[10:11], s[2:3], 0, v[10:11]
	s_mov_b64 s[2:3], 0
	v_readlane_b32 s37, v251, 18
	v_readlane_b32 s40, v251, 21
	v_readlane_b32 s41, v251, 22
	v_readlane_b32 s44, v251, 25
	v_readlane_b32 s45, v251, 26
	v_readlane_b32 s46, v251, 27
	v_readlane_b32 s47, v251, 28
	v_readlane_b32 s48, v251, 29
	v_readlane_b32 s49, v251, 30
	v_readlane_b32 s50, v251, 31
	v_readlane_b32 s51, v251, 32
	v_lshl_add_u64 v[12:13], v[8:9], 0, s[2:3]
	global_load_dwordx4 v[84:87], v[10:11], off offset:-24
	global_load_dwordx4 v[88:91], v[10:11], off offset:-8
	global_load_dword v68, v[12:13], off
	global_load_dword v69, v[12:13], off offset:256
	global_load_dword v70, v[12:13], off offset:512
	global_load_dword v71, v[12:13], off offset:768
	global_load_dword v72, v[12:13], off offset:1024
	global_load_dword v73, v[12:13], off offset:1280
	global_load_dword v74, v[12:13], off offset:1536
	global_load_dword v75, v[12:13], off offset:1792
	global_load_dword v76, v[12:13], off offset:2048
	global_load_dword v77, v[12:13], off offset:2304
	global_load_dword v78, v[12:13], off offset:2560
	global_load_dword v79, v[12:13], off offset:2816
	global_load_dword v80, v[12:13], off offset:3072
	global_load_dword v81, v[12:13], off offset:3328
	global_load_dword v82, v[12:13], off offset:3584
	global_load_dword v83, v[12:13], off offset:3840
	s_add_u32 s2, s2, 0x1000
	s_addc_u32 s3, s3, 0
	v_lshl_add_u64 v[10:11], v[10:11], 0, 32
; DI bf16_t f2bf(float a) { return (bf16_t)(pack2(a, 0.f) & 0xffffu); }
; DI float bflo(unsigned u) { return __uint_as_float(u << 16); }
; DI float bfhi(unsigned u) { return __uint_as_float(u & 0xffff0000u); }
; DI void phase4b(const Params& p, int layer) {
;     ...
;     float acc = 0.f;
;     for (int k8 = 0; k8 < 32; ++k8) {
;       uint4 hv = *(const uint4*)(hrow + k8 * 8);
;       const float* wr = w2 + (size_t)(k8 * 8) * 64 + lane;
;       acc += bflo(hv.x) * wr[0];
;       acc += bfhi(hv.x) * wr[64];
;       acc += bflo(hv.y) * wr[128];
;       acc += bfhi(hv.y) * wr[192];
;       acc += bflo(hv.z) * wr[256];
;       acc += bfhi(hv.z) * wr[320];
;       acc += bflo(hv.w) * wr[384];
;       acc += bfhi(hv.w) * wr[448];
;     }
;     if (kv == 0) {
;       float ss = wave_sum(acc * acc, lane);
;       float rs = rsqrtf(ss * (1.f / 64.f) + 1e-6f);
;       kcmp[(size_t)row * 64 + lane] = f2bf(acc * rs * kn[lane]);
;     } else {
;       const int bg = row >> 9, c = row & 511;
;       vcmpT[((size_t)(bg * 64 + lane)) * 512 + c] = f2bf(acc);
;     }
.LBB0_306:
	v_lshl_add_u64 v[12:13], v[8:9], 0, s[2:3]
	global_load_dwordx4 v[108:111], v[10:11], off offset:-24
	global_load_dwordx4 v[112:115], v[10:11], off offset:-8
	global_load_dword v92, v[12:13], off
	global_load_dword v93, v[12:13], off offset:256
	global_load_dword v94, v[12:13], off offset:512
	global_load_dword v95, v[12:13], off offset:768
	global_load_dword v96, v[12:13], off offset:1024
	global_load_dword v97, v[12:13], off offset:1280
	global_load_dword v98, v[12:13], off offset:1536
	global_load_dword v99, v[12:13], off offset:1792
	global_load_dword v100, v[12:13], off offset:2048
	global_load_dword v101, v[12:13], off offset:2304
	global_load_dword v102, v[12:13], off offset:2560
	global_load_dword v103, v[12:13], off offset:2816
	global_load_dword v104, v[12:13], off offset:3072
	global_load_dword v105, v[12:13], off offset:3328
	global_load_dword v106, v[12:13], off offset:3584
	global_load_dword v107, v[12:13], off offset:3840
	s_add_u32 s2, s2, 0x1000
	s_addc_u32 s3, s3, 0
	v_lshl_add_u64 v[10:11], v[10:11], 0, 32
	s_waitcnt vmcnt(18)
	v_lshlrev_b32_e32 v36, 16, v84
	v_fmac_f32_e32 v22, v68, v36
	v_and_b32_e32 v36, 0xffff0000, v84
	v_fmac_f32_e32 v22, v69, v36
	v_lshlrev_b32_e32 v36, 16, v85
	v_fmac_f32_e32 v22, v70, v36
	v_and_b32_e32 v36, 0xffff0000, v85
	v_fmac_f32_e32 v22, v71, v36
	v_lshlrev_b32_e32 v36, 16, v86
	v_fmac_f32_e32 v22, v72, v36
	v_and_b32_e32 v36, 0xffff0000, v86
	v_fmac_f32_e32 v22, v73, v36
	v_lshlrev_b32_e32 v36, 16, v87
	v_fmac_f32_e32 v22, v74, v36
	v_and_b32_e32 v36, 0xffff0000, v87
	v_fmac_f32_e32 v22, v75, v36
	v_lshlrev_b32_e32 v36, 16, v88
	v_fmac_f32_e32 v22, v76, v36
	v_and_b32_e32 v36, 0xffff0000, v88
	v_fmac_f32_e32 v22, v77, v36
	v_lshlrev_b32_e32 v36, 16, v89
	v_fmac_f32_e32 v22, v78, v36
	v_and_b32_e32 v36, 0xffff0000, v89
	v_fmac_f32_e32 v22, v79, v36
	v_lshlrev_b32_e32 v36, 16, v90
	v_fmac_f32_e32 v22, v80, v36
	v_and_b32_e32 v36, 0xffff0000, v90
	v_fmac_f32_e32 v22, v81, v36
	v_lshlrev_b32_e32 v36, 16, v91
	v_fmac_f32_e32 v22, v82, v36
	v_and_b32_e32 v36, 0xffff0000, v91
	v_fmac_f32_e32 v22, v83, v36
	s_cmp_eq_u32 s2, 0x10000
	s_cbranch_scc1 .Lc2_last
	v_lshl_add_u64 v[12:13], v[8:9], 0, s[2:3]
	global_load_dwordx4 v[84:87], v[10:11], off offset:-24
	global_load_dwordx4 v[88:91], v[10:11], off offset:-8
	global_load_dword v68, v[12:13], off
	global_load_dword v69, v[12:13], off offset:256
	global_load_dword v70, v[12:13], off offset:512
	global_load_dword v71, v[12:13], off offset:768
	global_load_dword v72, v[12:13], off offset:1024
	global_load_dword v73, v[12:13], off offset:1280
	global_load_dword v74, v[12:13], off offset:1536
	global_load_dword v75, v[12:13], off offset:1792
	global_load_dword v76, v[12:13], off offset:2048
	global_load_dword v77, v[12:13], off offset:2304
	global_load_dword v78, v[12:13], off offset:2560
	global_load_dword v79, v[12:13], off offset:2816
	global_load_dword v80, v[12:13], off offset:3072
	global_load_dword v81, v[12:13], off offset:3328
	global_load_dword v82, v[12:13], off offset:3584
	global_load_dword v83, v[12:13], off offset:3840
	s_add_u32 s2, s2, 0x1000
	s_addc_u32 s3, s3, 0
	v_lshl_add_u64 v[10:11], v[10:11], 0, 32
	s_waitcnt vmcnt(18)
	v_lshlrev_b32_e32 v36, 16, v108
	v_fmac_f32_e32 v22, v92, v36
	v_and_b32_e32 v36, 0xffff0000, v108
	v_fmac_f32_e32 v22, v93, v36
	v_lshlrev_b32_e32 v36, 16, v109
	v_fmac_f32_e32 v22, v94, v36
	v_and_b32_e32 v36, 0xffff0000, v109
	v_fmac_f32_e32 v22, v95, v36
	v_lshlrev_b32_e32 v36, 16, v110
	v_fmac_f32_e32 v22, v96, v36
	v_and_b32_e32 v36, 0xffff0000, v110
	v_fmac_f32_e32 v22, v97, v36
	v_lshlrev_b32_e32 v36, 16, v111
	v_fmac_f32_e32 v22, v98, v36
	v_and_b32_e32 v36, 0xffff0000, v111
	v_fmac_f32_e32 v22, v99, v36
	v_lshlrev_b32_e32 v36, 16, v112
	v_fmac_f32_e32 v22, v100, v36
	v_and_b32_e32 v36, 0xffff0000, v112
	v_fmac_f32_e32 v22, v101, v36
	v_lshlrev_b32_e32 v36, 16, v113
	v_fmac_f32_e32 v22, v102, v36
	v_and_b32_e32 v36, 0xffff0000, v113
	v_fmac_f32_e32 v22, v103, v36
	v_lshlrev_b32_e32 v36, 16, v114
	v_fmac_f32_e32 v22, v104, v36
	v_and_b32_e32 v36, 0xffff0000, v114
	v_fmac_f32_e32 v22, v105, v36
	v_lshlrev_b32_e32 v36, 16, v115
	v_fmac_f32_e32 v22, v106, v36
	v_and_b32_e32 v36, 0xffff0000, v115
	v_fmac_f32_e32 v22, v107, v36
	s_branch .LBB0_306
.Lc2_last:
	s_waitcnt vmcnt(0)
	v_lshlrev_b32_e32 v36, 16, v108
	v_fmac_f32_e32 v22, v92, v36
	v_and_b32_e32 v36, 0xffff0000, v108
	v_fmac_f32_e32 v22, v93, v36
	v_lshlrev_b32_e32 v36, 16, v109
	v_fmac_f32_e32 v22, v94, v36
	v_and_b32_e32 v36, 0xffff0000, v109
	v_fmac_f32_e32 v22, v95, v36
	v_lshlrev_b32_e32 v36, 16, v110
	v_fmac_f32_e32 v22, v96, v36
	v_and_b32_e32 v36, 0xffff0000, v110
	v_fmac_f32_e32 v22, v97, v36
	v_lshlrev_b32_e32 v36, 16, v111
	v_fmac_f32_e32 v22, v98, v36
	v_and_b32_e32 v36, 0xffff0000, v111
	v_fmac_f32_e32 v22, v99, v36
	v_lshlrev_b32_e32 v36, 16, v112
	v_fmac_f32_e32 v22, v100, v36
	v_and_b32_e32 v36, 0xffff0000, v112
	v_fmac_f32_e32 v22, v101, v36
	v_lshlrev_b32_e32 v36, 16, v113
	v_fmac_f32_e32 v22, v102, v36
	v_and_b32_e32 v36, 0xffff0000, v113
	v_fmac_f32_e32 v22, v103, v36
	v_lshlrev_b32_e32 v36, 16, v114
	v_fmac_f32_e32 v22, v104, v36
	v_and_b32_e32 v36, 0xffff0000, v114
	v_fmac_f32_e32 v22, v105, v36
	v_lshlrev_b32_e32 v36, 16, v115
	v_fmac_f32_e32 v22, v106, v36
	v_and_b32_e32 v36, 0xffff0000, v115
	v_fmac_f32_e32 v22, v107, v36
	s_and_saveexec_b64 s[2:3], vcc
	s_xor_b64 s[2:3], exec, s[2:3]
	s_cbranch_execz .LBB0_309
	v_and_b32_e32 v8, 0x1ff, v14
	v_lshrrev_b32_e32 v10, 3, v14
	s_movk_i32 s5, 0x1c0
	v_and_or_b32 v10, v10, s5, v2
	v_lshlrev_b32_e32 v8, 1, v8
	v_readlane_b32 s12, v252, 33
	v_cvt_pk_bf16_f32 v9, v22, s0
	v_lshl_or_b32 v8, v10, 10, v8
	v_readlane_b32 s13, v252, 34
	s_nop 4
	global_store_short v8, v9, s[12:13]
